# v3 + precomputed B-fragment LDS read base VGPR (no per-iteration VALU address adds)
# baseline (speedup 1.0000x reference)
.LBB0_340:
	v_add_u32_e32 v252, 0x10000, v159
	s_add_u32 s12, s12, 0x100080
	s_addc_u32 s13, s13, 0
	s_add_u32 s0, s14, 0x100
	v_mov_b32_e32 v2, 0
	s_addc_u32 s1, s15, 0
	s_mov_b32 s39, -2
	v_mov_b32_e32 v3, v2
	v_mov_b32_e32 v4, v2
	v_mov_b32_e32 v5, v2
	v_mov_b32_e32 v6, v2
	v_mov_b32_e32 v7, v2
	v_mov_b32_e32 v8, v2
	v_mov_b32_e32 v9, v2
	v_mov_b32_e32 v18, v2
	v_mov_b32_e32 v19, v2
	v_mov_b32_e32 v20, v2
	v_mov_b32_e32 v21, v2
	v_mov_b32_e32 v22, v2
	v_mov_b32_e32 v23, v2
	v_mov_b32_e32 v24, v2
	v_mov_b32_e32 v25, v2
	v_mov_b32_e32 v34, v2
	v_mov_b32_e32 v35, v2
	v_mov_b32_e32 v36, v2
	v_mov_b32_e32 v37, v2
	v_mov_b32_e32 v38, v2
	v_mov_b32_e32 v39, v2
	v_mov_b32_e32 v40, v2
	v_mov_b32_e32 v41, v2
	v_mov_b32_e32 v50, v2
	v_mov_b32_e32 v51, v2
	v_mov_b32_e32 v52, v2
	v_mov_b32_e32 v53, v2
	v_mov_b32_e32 v54, v2
	v_mov_b32_e32 v55, v2
	v_mov_b32_e32 v56, v2
	v_mov_b32_e32 v57, v2
	v_mov_b32_e32 v10, v2
	v_mov_b32_e32 v11, v2
	v_mov_b32_e32 v12, v2
	v_mov_b32_e32 v13, v2
	v_mov_b32_e32 v14, v2
	v_mov_b32_e32 v15, v2
	v_mov_b32_e32 v16, v2
	v_mov_b32_e32 v17, v2
	v_mov_b32_e32 v26, v2
	v_mov_b32_e32 v27, v2
	v_mov_b32_e32 v28, v2
	v_mov_b32_e32 v29, v2
	v_mov_b32_e32 v30, v2
	v_mov_b32_e32 v31, v2
	v_mov_b32_e32 v32, v2
	v_mov_b32_e32 v33, v2
	v_mov_b32_e32 v42, v2
	v_mov_b32_e32 v43, v2
	v_mov_b32_e32 v44, v2
	v_mov_b32_e32 v45, v2
	v_mov_b32_e32 v46, v2
	v_mov_b32_e32 v47, v2
	v_mov_b32_e32 v48, v2
	v_mov_b32_e32 v49, v2
	v_mov_b32_e32 v58, v2
	v_mov_b32_e32 v59, v2
	v_mov_b32_e32 v60, v2
	v_mov_b32_e32 v61, v2
	v_mov_b32_e32 v62, v2
	v_mov_b32_e32 v63, v2
	v_mov_b32_e32 v64, v2
	v_mov_b32_e32 v65, v2
	v_mov_b32_e32 v66, v2
	v_mov_b32_e32 v67, v2
	v_mov_b32_e32 v68, v2
	v_mov_b32_e32 v69, v2
	v_mov_b32_e32 v70, v2
	v_mov_b32_e32 v71, v2
	v_mov_b32_e32 v72, v2
	v_mov_b32_e32 v73, v2
	v_mov_b32_e32 v82, v2
	v_mov_b32_e32 v83, v2
	v_mov_b32_e32 v84, v2
	v_mov_b32_e32 v85, v2
	v_mov_b32_e32 v86, v2
	v_mov_b32_e32 v87, v2
	v_mov_b32_e32 v88, v2
	v_mov_b32_e32 v89, v2
	v_mov_b32_e32 v98, v2
	v_mov_b32_e32 v99, v2
	v_mov_b32_e32 v100, v2
	v_mov_b32_e32 v101, v2
	v_mov_b32_e32 v102, v2
	v_mov_b32_e32 v103, v2
	v_mov_b32_e32 v104, v2
	v_mov_b32_e32 v105, v2
	v_mov_b32_e32 v114, v2
	v_mov_b32_e32 v115, v2
	v_mov_b32_e32 v116, v2
	v_mov_b32_e32 v117, v2
	v_mov_b32_e32 v118, v2
	v_mov_b32_e32 v119, v2
	v_mov_b32_e32 v120, v2
	v_mov_b32_e32 v121, v2
	v_mov_b32_e32 v74, v2
	v_mov_b32_e32 v75, v2
	v_mov_b32_e32 v76, v2
	v_mov_b32_e32 v77, v2
	v_mov_b32_e32 v78, v2
	v_mov_b32_e32 v79, v2
	v_mov_b32_e32 v80, v2
	v_mov_b32_e32 v81, v2
	v_mov_b32_e32 v90, v2
	v_mov_b32_e32 v91, v2
	v_mov_b32_e32 v92, v2
	v_mov_b32_e32 v93, v2
	v_mov_b32_e32 v94, v2
	v_mov_b32_e32 v95, v2
	v_mov_b32_e32 v96, v2
	v_mov_b32_e32 v97, v2
	v_mov_b32_e32 v106, v2
	v_mov_b32_e32 v107, v2
	v_mov_b32_e32 v108, v2
	v_mov_b32_e32 v109, v2
	v_mov_b32_e32 v110, v2
	v_mov_b32_e32 v111, v2
	v_mov_b32_e32 v112, v2
	v_mov_b32_e32 v113, v2
	v_mov_b32_e32 v122, v2
	v_mov_b32_e32 v123, v2
	v_mov_b32_e32 v124, v2
	v_mov_b32_e32 v125, v2
	v_mov_b32_e32 v126, v2
	v_mov_b32_e32 v127, v2
	v_mov_b32_e32 v128, v2
	v_mov_b32_e32 v129, v2
.LBB0_341:
	s_add_u32 s14, s12, 0xfff00080
	s_addc_u32 s15, s13, -1
	s_cmp_eq_u32 s39, 60
	s_cselect_b32 s17, s51, s15
	s_cselect_b32 s16, s50, s14
	s_cselect_b32 s15, s53, s1
	s_cselect_b32 s14, s52, s0
	s_add_i32 m0, s8, 0xc000
	ds_read_b128 v[152:155], v252
	ds_read_b128 v[162:165], v252 offset:1024
	global_load_lds_dwordx4 v148, s[12:13]
	s_add_i32 m0, s8, 0xe000
	ds_read_b128 v[166:169], v252 offset:2048
	ds_read_b128 v[170:173], v252 offset:3072
	global_load_lds_dwordx4 v150, s[12:13]
	ds_read_b128 v[174:177], v252 offset:16384
	ds_read_b128 v[182:185], v252 offset:17408
	ds_read_b128 v[186:189], v252 offset:18432
	ds_read_b128 v[190:193], v252 offset:19456
	ds_read_b128 v[194:197], v161
	ds_read_b128 v[198:201], v161 offset:1024
	ds_read_b128 v[202:205], v161 offset:2048
	ds_read_b128 v[206:209], v161 offset:3072
	ds_read_b128 v[210:213], v161 offset:4096
	ds_read_b128 v[214:217], v161 offset:5120
	ds_read_b128 v[218:221], v161 offset:6144
	ds_read_b128 v[222:225], v161 offset:7168
	s_waitcnt vmcnt(8)
	s_waitcnt lgkmcnt(0)
	s_barrier
	v_mfma_f32_16x16x32_bf16 v[126:129], v[152:155], v[194:197], v[126:129]
	v_mfma_f32_16x16x32_bf16 v[126:129], v[162:165], v[198:201], v[126:129]
	v_mfma_f32_16x16x32_bf16 v[122:125], v[166:169], v[194:197], v[122:125]
	v_mfma_f32_16x16x32_bf16 v[122:125], v[170:173], v[198:201], v[122:125]
	v_mfma_f32_16x16x32_bf16 v[110:113], v[152:155], v[202:205], v[110:113]
	v_mfma_f32_16x16x32_bf16 v[110:113], v[162:165], v[206:209], v[110:113]
	v_mfma_f32_16x16x32_bf16 v[106:109], v[166:169], v[202:205], v[106:109]
	v_mfma_f32_16x16x32_bf16 v[106:109], v[170:173], v[206:209], v[106:109]
	v_mfma_f32_16x16x32_bf16 v[94:97], v[152:155], v[210:213], v[94:97]
	v_mfma_f32_16x16x32_bf16 v[94:97], v[162:165], v[214:217], v[94:97]
	v_mfma_f32_16x16x32_bf16 v[90:93], v[166:169], v[210:213], v[90:93]
	v_mfma_f32_16x16x32_bf16 v[90:93], v[170:173], v[214:217], v[90:93]
	v_mfma_f32_16x16x32_bf16 v[78:81], v[152:155], v[218:221], v[78:81]
	v_mfma_f32_16x16x32_bf16 v[78:81], v[162:165], v[222:225], v[78:81]
	v_mfma_f32_16x16x32_bf16 v[74:77], v[166:169], v[218:221], v[74:77]
	v_mfma_f32_16x16x32_bf16 v[74:77], v[170:173], v[222:225], v[74:77]
	v_mfma_f32_16x16x32_bf16 v[118:121], v[174:177], v[194:197], v[118:121]
	v_mfma_f32_16x16x32_bf16 v[118:121], v[182:185], v[198:201], v[118:121]
	v_mfma_f32_16x16x32_bf16 v[114:117], v[186:189], v[194:197], v[114:117]
	v_mfma_f32_16x16x32_bf16 v[114:117], v[190:193], v[198:201], v[114:117]
	v_mfma_f32_16x16x32_bf16 v[102:105], v[174:177], v[202:205], v[102:105]
	v_mfma_f32_16x16x32_bf16 v[102:105], v[182:185], v[206:209], v[102:105]
	v_mfma_f32_16x16x32_bf16 v[98:101], v[186:189], v[202:205], v[98:101]
	v_mfma_f32_16x16x32_bf16 v[98:101], v[190:193], v[206:209], v[98:101]
	v_mfma_f32_16x16x32_bf16 v[86:89], v[174:177], v[210:213], v[86:89]
	v_mfma_f32_16x16x32_bf16 v[86:89], v[182:185], v[214:217], v[86:89]
	v_mfma_f32_16x16x32_bf16 v[82:85], v[186:189], v[210:213], v[82:85]
	v_mfma_f32_16x16x32_bf16 v[82:85], v[190:193], v[214:217], v[82:85]
	v_mfma_f32_16x16x32_bf16 v[70:73], v[174:177], v[218:221], v[70:73]
	v_mfma_f32_16x16x32_bf16 v[70:73], v[182:185], v[222:225], v[70:73]
	v_mfma_f32_16x16x32_bf16 v[66:69], v[186:189], v[218:221], v[66:69]
	v_mfma_f32_16x16x32_bf16 v[66:69], v[190:193], v[222:225], v[66:69]
	s_barrier
	s_add_i32 m0, s28, 0x10000
	ds_read_b128 v[194:197], v161 offset:16384
	ds_read_b128 v[198:201], v161 offset:17408
	global_load_lds_dwordx4 v144, s[14:15]
	s_add_i32 m0, s28, 0x12000
	s_add_u32 s98, s14, 0x100000
	s_addc_u32 s99, s15, 0
	ds_read_b128 v[202:205], v161 offset:18432
	global_load_lds_dwordx4 v140, s[14:15]
	s_add_i32 m0, s28, 0x14000
	ds_read_b128 v[206:209], v161 offset:19456
	ds_read_b128 v[210:213], v161 offset:20480
	global_load_lds_dwordx4 v144, s[98:99]
	s_add_i32 m0, s28, 0x16000
	ds_read_b128 v[214:217], v161 offset:21504
	ds_read_b128 v[218:221], v161 offset:22528
	global_load_lds_dwordx4 v140, s[98:99]
	s_mov_b32 m0, s8
	ds_read_b128 v[222:225], v161 offset:23552
	global_load_lds_dwordx4 v146, s[16:17]
	s_mov_b32 m0, s9
	s_nop 0
	global_load_lds_dwordx4 v142, s[16:17]
	s_waitcnt vmcnt(8)
	s_waitcnt lgkmcnt(0)
	s_barrier
	v_mfma_f32_16x16x32_bf16 v[62:65], v[152:155], v[194:197], v[62:65]
	v_mfma_f32_16x16x32_bf16 v[62:65], v[162:165], v[198:201], v[62:65]
	v_mfma_f32_16x16x32_bf16 v[58:61], v[166:169], v[194:197], v[58:61]
	v_mfma_f32_16x16x32_bf16 v[58:61], v[170:173], v[198:201], v[58:61]
	v_mfma_f32_16x16x32_bf16 v[46:49], v[152:155], v[202:205], v[46:49]
	v_mfma_f32_16x16x32_bf16 v[46:49], v[162:165], v[206:209], v[46:49]
	v_mfma_f32_16x16x32_bf16 v[42:45], v[166:169], v[202:205], v[42:45]
	v_mfma_f32_16x16x32_bf16 v[42:45], v[170:173], v[206:209], v[42:45]
	v_mfma_f32_16x16x32_bf16 v[30:33], v[152:155], v[210:213], v[30:33]
	v_mfma_f32_16x16x32_bf16 v[30:33], v[162:165], v[214:217], v[30:33]
	v_mfma_f32_16x16x32_bf16 v[26:29], v[166:169], v[210:213], v[26:29]
	v_mfma_f32_16x16x32_bf16 v[26:29], v[170:173], v[214:217], v[26:29]
	v_mfma_f32_16x16x32_bf16 v[14:17], v[152:155], v[218:221], v[14:17]
	v_mfma_f32_16x16x32_bf16 v[14:17], v[162:165], v[222:225], v[14:17]
	v_mfma_f32_16x16x32_bf16 v[10:13], v[166:169], v[218:221], v[10:13]
	v_mfma_f32_16x16x32_bf16 v[10:13], v[170:173], v[222:225], v[10:13]
	v_mfma_f32_16x16x32_bf16 v[54:57], v[174:177], v[194:197], v[54:57]
	v_mfma_f32_16x16x32_bf16 v[54:57], v[182:185], v[198:201], v[54:57]
	v_mfma_f32_16x16x32_bf16 v[50:53], v[186:189], v[194:197], v[50:53]
	v_mfma_f32_16x16x32_bf16 v[50:53], v[190:193], v[198:201], v[50:53]
	v_mfma_f32_16x16x32_bf16 v[38:41], v[174:177], v[202:205], v[38:41]
	v_mfma_f32_16x16x32_bf16 v[38:41], v[182:185], v[206:209], v[38:41]
	v_mfma_f32_16x16x32_bf16 v[34:37], v[186:189], v[202:205], v[34:37]
	v_mfma_f32_16x16x32_bf16 v[34:37], v[190:193], v[206:209], v[34:37]
	v_mfma_f32_16x16x32_bf16 v[22:25], v[174:177], v[210:213], v[22:25]
	v_mfma_f32_16x16x32_bf16 v[22:25], v[182:185], v[214:217], v[22:25]
	v_mfma_f32_16x16x32_bf16 v[18:21], v[186:189], v[210:213], v[18:21]
	v_mfma_f32_16x16x32_bf16 v[18:21], v[190:193], v[214:217], v[18:21]
	v_mfma_f32_16x16x32_bf16 v[6:9], v[174:177], v[218:221], v[6:9]
	v_mfma_f32_16x16x32_bf16 v[6:9], v[182:185], v[222:225], v[6:9]
	v_mfma_f32_16x16x32_bf16 v[2:5], v[186:189], v[218:221], v[2:5]
	v_mfma_f32_16x16x32_bf16 v[2:5], v[190:193], v[222:225], v[2:5]
	s_barrier
	s_add_u32 s100, s16, 0x100000
	s_addc_u32 s101, s17, 0
	s_mov_b32 m0, s29
	ds_read_b128 v[152:155], v252 offset:32768
	ds_read_b128 v[162:165], v252 offset:33792
	global_load_lds_dwordx4 v146, s[100:101]
	s_mov_b32 m0, s36
	ds_read_b128 v[166:169], v252 offset:34816
	ds_read_b128 v[170:173], v252 offset:35840
	global_load_lds_dwordx4 v142, s[100:101]
	ds_read_b128 v[174:177], v252 offset:49152
	ds_read_b128 v[182:185], v252 offset:50176
	ds_read_b128 v[186:189], v252 offset:51200
	ds_read_b128 v[190:193], v252 offset:52224
	ds_read_b128 v[194:197], v161 offset:32768
	ds_read_b128 v[198:201], v161 offset:33792
	ds_read_b128 v[202:205], v161 offset:34816
	ds_read_b128 v[206:209], v161 offset:35840
	ds_read_b128 v[210:213], v161 offset:36864
	ds_read_b128 v[214:217], v161 offset:37888
	ds_read_b128 v[218:221], v161 offset:38912
	ds_read_b128 v[222:225], v161 offset:39936
	s_waitcnt vmcnt(8)
	s_waitcnt lgkmcnt(0)
	s_barrier
	v_mfma_f32_16x16x32_bf16 v[126:129], v[152:155], v[194:197], v[126:129]
	v_mfma_f32_16x16x32_bf16 v[126:129], v[162:165], v[198:201], v[126:129]
	v_mfma_f32_16x16x32_bf16 v[122:125], v[166:169], v[194:197], v[122:125]
	v_mfma_f32_16x16x32_bf16 v[122:125], v[170:173], v[198:201], v[122:125]
	v_mfma_f32_16x16x32_bf16 v[110:113], v[152:155], v[202:205], v[110:113]
	v_mfma_f32_16x16x32_bf16 v[110:113], v[162:165], v[206:209], v[110:113]
	v_mfma_f32_16x16x32_bf16 v[106:109], v[166:169], v[202:205], v[106:109]
	v_mfma_f32_16x16x32_bf16 v[106:109], v[170:173], v[206:209], v[106:109]
	v_mfma_f32_16x16x32_bf16 v[94:97], v[152:155], v[210:213], v[94:97]
	v_mfma_f32_16x16x32_bf16 v[94:97], v[162:165], v[214:217], v[94:97]
	v_mfma_f32_16x16x32_bf16 v[90:93], v[166:169], v[210:213], v[90:93]
	v_mfma_f32_16x16x32_bf16 v[90:93], v[170:173], v[214:217], v[90:93]
	v_mfma_f32_16x16x32_bf16 v[78:81], v[152:155], v[218:221], v[78:81]
	v_mfma_f32_16x16x32_bf16 v[78:81], v[162:165], v[222:225], v[78:81]
	v_mfma_f32_16x16x32_bf16 v[74:77], v[166:169], v[218:221], v[74:77]
	v_mfma_f32_16x16x32_bf16 v[74:77], v[170:173], v[222:225], v[74:77]
	v_mfma_f32_16x16x32_bf16 v[118:121], v[174:177], v[194:197], v[118:121]
	v_mfma_f32_16x16x32_bf16 v[118:121], v[182:185], v[198:201], v[118:121]
	v_mfma_f32_16x16x32_bf16 v[114:117], v[186:189], v[194:197], v[114:117]
	v_mfma_f32_16x16x32_bf16 v[114:117], v[190:193], v[198:201], v[114:117]
	v_mfma_f32_16x16x32_bf16 v[102:105], v[174:177], v[202:205], v[102:105]
	v_mfma_f32_16x16x32_bf16 v[102:105], v[182:185], v[206:209], v[102:105]
	v_mfma_f32_16x16x32_bf16 v[98:101], v[186:189], v[202:205], v[98:101]
	v_mfma_f32_16x16x32_bf16 v[98:101], v[190:193], v[206:209], v[98:101]
	v_mfma_f32_16x16x32_bf16 v[86:89], v[174:177], v[210:213], v[86:89]
	v_mfma_f32_16x16x32_bf16 v[86:89], v[182:185], v[214:217], v[86:89]
	v_mfma_f32_16x16x32_bf16 v[82:85], v[186:189], v[210:213], v[82:85]
	v_mfma_f32_16x16x32_bf16 v[82:85], v[190:193], v[214:217], v[82:85]
	v_mfma_f32_16x16x32_bf16 v[70:73], v[174:177], v[218:221], v[70:73]
	v_mfma_f32_16x16x32_bf16 v[70:73], v[182:185], v[222:225], v[70:73]
	v_mfma_f32_16x16x32_bf16 v[66:69], v[186:189], v[218:221], v[66:69]
	v_mfma_f32_16x16x32_bf16 v[66:69], v[190:193], v[222:225], v[66:69]
	s_barrier
	s_add_u32 s14, s14, 0x80
	s_addc_u32 s15, s15, 0
	s_add_i32 m0, s28, 0x18000
	ds_read_b128 v[194:197], v161 offset:49152
	ds_read_b128 v[198:201], v161 offset:50176
	global_load_lds_dwordx4 v144, s[14:15]
	s_add_i32 m0, s28, 0x1a000
	s_add_u32 s98, s98, 0x80
	s_addc_u32 s99, s99, 0
	ds_read_b128 v[202:205], v161 offset:51200
	global_load_lds_dwordx4 v140, s[14:15]
	s_add_i32 m0, s28, 0x1c000
	ds_read_b128 v[206:209], v161 offset:52224
	ds_read_b128 v[210:213], v161 offset:53248
	global_load_lds_dwordx4 v144, s[98:99]
	s_add_i32 m0, s28, 0x1e000
	s_add_u32 s16, s16, 0x80
	s_addc_u32 s17, s17, 0
	ds_read_b128 v[214:217], v161 offset:54272
	ds_read_b128 v[218:221], v161 offset:55296
	global_load_lds_dwordx4 v140, s[98:99]
	s_mov_b32 m0, s45
	ds_read_b128 v[222:225], v161 offset:56320
	global_load_lds_dwordx4 v146, s[16:17]
	s_mov_b32 m0, s46
	s_nop 0
	global_load_lds_dwordx4 v142, s[16:17]
	s_waitcnt vmcnt(8)
	s_waitcnt lgkmcnt(0)
	s_barrier
	v_mfma_f32_16x16x32_bf16 v[62:65], v[152:155], v[194:197], v[62:65]
	v_mfma_f32_16x16x32_bf16 v[62:65], v[162:165], v[198:201], v[62:65]
	v_mfma_f32_16x16x32_bf16 v[58:61], v[166:169], v[194:197], v[58:61]
	v_mfma_f32_16x16x32_bf16 v[58:61], v[170:173], v[198:201], v[58:61]
	v_mfma_f32_16x16x32_bf16 v[46:49], v[152:155], v[202:205], v[46:49]
	v_mfma_f32_16x16x32_bf16 v[46:49], v[162:165], v[206:209], v[46:49]
	v_mfma_f32_16x16x32_bf16 v[42:45], v[166:169], v[202:205], v[42:45]
	v_mfma_f32_16x16x32_bf16 v[42:45], v[170:173], v[206:209], v[42:45]
	v_mfma_f32_16x16x32_bf16 v[30:33], v[152:155], v[210:213], v[30:33]
	v_mfma_f32_16x16x32_bf16 v[30:33], v[162:165], v[214:217], v[30:33]
	v_mfma_f32_16x16x32_bf16 v[26:29], v[166:169], v[210:213], v[26:29]
	v_mfma_f32_16x16x32_bf16 v[26:29], v[170:173], v[214:217], v[26:29]
	v_mfma_f32_16x16x32_bf16 v[14:17], v[152:155], v[218:221], v[14:17]
	v_mfma_f32_16x16x32_bf16 v[14:17], v[162:165], v[222:225], v[14:17]
	v_mfma_f32_16x16x32_bf16 v[10:13], v[166:169], v[218:221], v[10:13]
	v_mfma_f32_16x16x32_bf16 v[10:13], v[170:173], v[222:225], v[10:13]
	v_mfma_f32_16x16x32_bf16 v[54:57], v[174:177], v[194:197], v[54:57]
	v_mfma_f32_16x16x32_bf16 v[54:57], v[182:185], v[198:201], v[54:57]
	v_mfma_f32_16x16x32_bf16 v[50:53], v[186:189], v[194:197], v[50:53]
	v_mfma_f32_16x16x32_bf16 v[50:53], v[190:193], v[198:201], v[50:53]
	v_mfma_f32_16x16x32_bf16 v[38:41], v[174:177], v[202:205], v[38:41]
	v_mfma_f32_16x16x32_bf16 v[38:41], v[182:185], v[206:209], v[38:41]
	v_mfma_f32_16x16x32_bf16 v[34:37], v[186:189], v[202:205], v[34:37]
	v_mfma_f32_16x16x32_bf16 v[34:37], v[190:193], v[206:209], v[34:37]
	v_mfma_f32_16x16x32_bf16 v[22:25], v[174:177], v[210:213], v[22:25]
	v_mfma_f32_16x16x32_bf16 v[22:25], v[182:185], v[214:217], v[22:25]
	v_mfma_f32_16x16x32_bf16 v[18:21], v[186:189], v[210:213], v[18:21]
	v_mfma_f32_16x16x32_bf16 v[18:21], v[190:193], v[214:217], v[18:21]
	v_mfma_f32_16x16x32_bf16 v[6:9], v[174:177], v[218:221], v[6:9]
	v_mfma_f32_16x16x32_bf16 v[6:9], v[182:185], v[222:225], v[6:9]
	v_mfma_f32_16x16x32_bf16 v[2:5], v[186:189], v[218:221], v[2:5]
	v_mfma_f32_16x16x32_bf16 v[2:5], v[190:193], v[222:225], v[2:5]
	s_barrier
	s_add_i32 s39, s39, 2
	s_add_u32 s12, s12, 0x100
	s_addc_u32 s13, s13, 0
	s_add_u32 s0, s0, 0x100
	s_addc_u32 s1, s1, 0
	s_cmp_gt_u32 s39, 61
	s_cbranch_scc0 .LBB0_341
	s_and_b64 vcc, exec, s[34:35]
	s_cbranch_vccz .LBB0_344
	s_barrier

.LBB0_571:
	v_add_u32_e32 v252, 0x10000, v159
	s_add_u32 s12, s12, 0x100080
	s_addc_u32 s13, s13, 0
	s_add_u32 s0, s14, 0x100
	v_mov_b32_e32 v2, 0
	s_addc_u32 s1, s15, 0
	s_mov_b32 s35, -2
	v_mov_b32_e32 v3, v2
	v_mov_b32_e32 v4, v2
	v_mov_b32_e32 v5, v2
	v_mov_b32_e32 v6, v2
	v_mov_b32_e32 v7, v2
	v_mov_b32_e32 v8, v2
	v_mov_b32_e32 v9, v2
	v_mov_b32_e32 v18, v2
	v_mov_b32_e32 v19, v2
	v_mov_b32_e32 v20, v2
	v_mov_b32_e32 v21, v2
	v_mov_b32_e32 v22, v2
	v_mov_b32_e32 v23, v2
	v_mov_b32_e32 v24, v2
	v_mov_b32_e32 v25, v2
	v_mov_b32_e32 v34, v2
	v_mov_b32_e32 v35, v2
	v_mov_b32_e32 v36, v2
	v_mov_b32_e32 v37, v2
	v_mov_b32_e32 v38, v2
	v_mov_b32_e32 v39, v2
	v_mov_b32_e32 v40, v2
	v_mov_b32_e32 v41, v2
	v_mov_b32_e32 v50, v2
	v_mov_b32_e32 v51, v2
	v_mov_b32_e32 v52, v2
	v_mov_b32_e32 v53, v2
	v_mov_b32_e32 v54, v2
	v_mov_b32_e32 v55, v2
	v_mov_b32_e32 v56, v2
	v_mov_b32_e32 v57, v2
	v_mov_b32_e32 v10, v2
	v_mov_b32_e32 v11, v2
	v_mov_b32_e32 v12, v2
	v_mov_b32_e32 v13, v2
	v_mov_b32_e32 v14, v2
	v_mov_b32_e32 v15, v2
	v_mov_b32_e32 v16, v2
	v_mov_b32_e32 v17, v2
	v_mov_b32_e32 v26, v2
	v_mov_b32_e32 v27, v2
	v_mov_b32_e32 v28, v2
	v_mov_b32_e32 v29, v2
	v_mov_b32_e32 v30, v2
	v_mov_b32_e32 v31, v2
	v_mov_b32_e32 v32, v2
	v_mov_b32_e32 v33, v2
	v_mov_b32_e32 v42, v2
	v_mov_b32_e32 v43, v2
	v_mov_b32_e32 v44, v2
	v_mov_b32_e32 v45, v2
	v_mov_b32_e32 v46, v2
	v_mov_b32_e32 v47, v2
	v_mov_b32_e32 v48, v2
	v_mov_b32_e32 v49, v2
	v_mov_b32_e32 v58, v2
	v_mov_b32_e32 v59, v2
	v_mov_b32_e32 v60, v2
	v_mov_b32_e32 v61, v2
	v_mov_b32_e32 v62, v2
	v_mov_b32_e32 v63, v2
	v_mov_b32_e32 v64, v2
	v_mov_b32_e32 v65, v2
	v_mov_b32_e32 v66, v2
	v_mov_b32_e32 v67, v2
	v_mov_b32_e32 v68, v2
	v_mov_b32_e32 v69, v2
	v_mov_b32_e32 v70, v2
	v_mov_b32_e32 v71, v2
	v_mov_b32_e32 v72, v2
	v_mov_b32_e32 v73, v2
	v_mov_b32_e32 v82, v2
	v_mov_b32_e32 v83, v2
	v_mov_b32_e32 v84, v2
	v_mov_b32_e32 v85, v2
	v_mov_b32_e32 v86, v2
	v_mov_b32_e32 v87, v2
	v_mov_b32_e32 v88, v2
	v_mov_b32_e32 v89, v2
	v_mov_b32_e32 v98, v2
	v_mov_b32_e32 v99, v2
	v_mov_b32_e32 v100, v2
	v_mov_b32_e32 v101, v2
	v_mov_b32_e32 v102, v2
	v_mov_b32_e32 v103, v2
	v_mov_b32_e32 v104, v2
	v_mov_b32_e32 v105, v2
	v_mov_b32_e32 v114, v2
	v_mov_b32_e32 v115, v2
	v_mov_b32_e32 v116, v2
	v_mov_b32_e32 v117, v2
	v_mov_b32_e32 v118, v2
	v_mov_b32_e32 v119, v2
	v_mov_b32_e32 v120, v2
	v_mov_b32_e32 v121, v2
	v_mov_b32_e32 v74, v2
	v_mov_b32_e32 v75, v2
	v_mov_b32_e32 v76, v2
	v_mov_b32_e32 v77, v2
	v_mov_b32_e32 v78, v2
	v_mov_b32_e32 v79, v2
	v_mov_b32_e32 v80, v2
	v_mov_b32_e32 v81, v2
	v_mov_b32_e32 v90, v2
	v_mov_b32_e32 v91, v2
	v_mov_b32_e32 v92, v2
	v_mov_b32_e32 v93, v2
	v_mov_b32_e32 v94, v2
	v_mov_b32_e32 v95, v2
	v_mov_b32_e32 v96, v2
	v_mov_b32_e32 v97, v2
	v_mov_b32_e32 v106, v2
	v_mov_b32_e32 v107, v2
	v_mov_b32_e32 v108, v2
	v_mov_b32_e32 v109, v2
	v_mov_b32_e32 v110, v2
	v_mov_b32_e32 v111, v2
	v_mov_b32_e32 v112, v2
	v_mov_b32_e32 v113, v2
	v_mov_b32_e32 v122, v2
	v_mov_b32_e32 v123, v2
	v_mov_b32_e32 v124, v2
	v_mov_b32_e32 v125, v2
	v_mov_b32_e32 v126, v2
	v_mov_b32_e32 v127, v2
	v_mov_b32_e32 v128, v2
	v_mov_b32_e32 v129, v2
.LBB0_572:
	s_add_u32 s14, s12, 0xfff00080
	s_addc_u32 s15, s13, -1
	s_cmp_eq_u32 s35, 60
	s_cselect_b32 s17, s51, s15
	s_cselect_b32 s16, s50, s14
	s_cselect_b32 s15, s53, s1
	s_cselect_b32 s14, s52, s0
	s_add_i32 m0, s8, 0xc000
	ds_read_b128 v[152:155], v252
	ds_read_b128 v[162:165], v252 offset:1024
	global_load_lds_dwordx4 v148, s[12:13]
	s_add_i32 m0, s8, 0xe000
	ds_read_b128 v[166:169], v252 offset:2048
	ds_read_b128 v[170:173], v252 offset:3072
	global_load_lds_dwordx4 v150, s[12:13]
	ds_read_b128 v[174:177], v252 offset:16384
	ds_read_b128 v[182:185], v252 offset:17408
	ds_read_b128 v[186:189], v252 offset:18432
	ds_read_b128 v[190:193], v252 offset:19456
	ds_read_b128 v[194:197], v161
	ds_read_b128 v[198:201], v161 offset:1024
	ds_read_b128 v[202:205], v161 offset:2048
	ds_read_b128 v[206:209], v161 offset:3072
	ds_read_b128 v[210:213], v161 offset:4096
	ds_read_b128 v[214:217], v161 offset:5120
	ds_read_b128 v[218:221], v161 offset:6144
	ds_read_b128 v[222:225], v161 offset:7168
	s_waitcnt vmcnt(8)
	s_waitcnt lgkmcnt(0)
	s_barrier
	v_mfma_f32_16x16x32_bf16 v[126:129], v[152:155], v[194:197], v[126:129]
	v_mfma_f32_16x16x32_bf16 v[126:129], v[162:165], v[198:201], v[126:129]
	v_mfma_f32_16x16x32_bf16 v[122:125], v[166:169], v[194:197], v[122:125]
	v_mfma_f32_16x16x32_bf16 v[122:125], v[170:173], v[198:201], v[122:125]
	v_mfma_f32_16x16x32_bf16 v[110:113], v[152:155], v[202:205], v[110:113]
	v_mfma_f32_16x16x32_bf16 v[110:113], v[162:165], v[206:209], v[110:113]
	v_mfma_f32_16x16x32_bf16 v[106:109], v[166:169], v[202:205], v[106:109]
	v_mfma_f32_16x16x32_bf16 v[106:109], v[170:173], v[206:209], v[106:109]
	v_mfma_f32_16x16x32_bf16 v[94:97], v[152:155], v[210:213], v[94:97]
	v_mfma_f32_16x16x32_bf16 v[94:97], v[162:165], v[214:217], v[94:97]
	v_mfma_f32_16x16x32_bf16 v[90:93], v[166:169], v[210:213], v[90:93]
	v_mfma_f32_16x16x32_bf16 v[90:93], v[170:173], v[214:217], v[90:93]
	v_mfma_f32_16x16x32_bf16 v[78:81], v[152:155], v[218:221], v[78:81]
	v_mfma_f32_16x16x32_bf16 v[78:81], v[162:165], v[222:225], v[78:81]
	v_mfma_f32_16x16x32_bf16 v[74:77], v[166:169], v[218:221], v[74:77]
	v_mfma_f32_16x16x32_bf16 v[74:77], v[170:173], v[222:225], v[74:77]
	v_mfma_f32_16x16x32_bf16 v[118:121], v[174:177], v[194:197], v[118:121]
	v_mfma_f32_16x16x32_bf16 v[118:121], v[182:185], v[198:201], v[118:121]
	v_mfma_f32_16x16x32_bf16 v[114:117], v[186:189], v[194:197], v[114:117]
	v_mfma_f32_16x16x32_bf16 v[114:117], v[190:193], v[198:201], v[114:117]
	v_mfma_f32_16x16x32_bf16 v[102:105], v[174:177], v[202:205], v[102:105]
	v_mfma_f32_16x16x32_bf16 v[102:105], v[182:185], v[206:209], v[102:105]
	v_mfma_f32_16x16x32_bf16 v[98:101], v[186:189], v[202:205], v[98:101]
	v_mfma_f32_16x16x32_bf16 v[98:101], v[190:193], v[206:209], v[98:101]
	v_mfma_f32_16x16x32_bf16 v[86:89], v[174:177], v[210:213], v[86:89]
	v_mfma_f32_16x16x32_bf16 v[86:89], v[182:185], v[214:217], v[86:89]
	v_mfma_f32_16x16x32_bf16 v[82:85], v[186:189], v[210:213], v[82:85]
	v_mfma_f32_16x16x32_bf16 v[82:85], v[190:193], v[214:217], v[82:85]
	v_mfma_f32_16x16x32_bf16 v[70:73], v[174:177], v[218:221], v[70:73]
	v_mfma_f32_16x16x32_bf16 v[70:73], v[182:185], v[222:225], v[70:73]
	v_mfma_f32_16x16x32_bf16 v[66:69], v[186:189], v[218:221], v[66:69]
	v_mfma_f32_16x16x32_bf16 v[66:69], v[190:193], v[222:225], v[66:69]
	s_barrier
	s_add_i32 m0, s28, 0x10000
	ds_read_b128 v[194:197], v161 offset:16384
	ds_read_b128 v[198:201], v161 offset:17408
	global_load_lds_dwordx4 v144, s[14:15]
	s_add_i32 m0, s28, 0x12000
	s_add_u32 s98, s14, 0x100000
	s_addc_u32 s99, s15, 0
	ds_read_b128 v[202:205], v161 offset:18432
	global_load_lds_dwordx4 v140, s[14:15]
	s_add_i32 m0, s28, 0x14000
	ds_read_b128 v[206:209], v161 offset:19456
	ds_read_b128 v[210:213], v161 offset:20480
	global_load_lds_dwordx4 v144, s[98:99]
	s_add_i32 m0, s28, 0x16000
	ds_read_b128 v[214:217], v161 offset:21504
	ds_read_b128 v[218:221], v161 offset:22528
	global_load_lds_dwordx4 v140, s[98:99]
	s_mov_b32 m0, s8
	ds_read_b128 v[222:225], v161 offset:23552
	global_load_lds_dwordx4 v146, s[16:17]
	s_mov_b32 m0, s9
	s_nop 0
	global_load_lds_dwordx4 v142, s[16:17]
	s_waitcnt vmcnt(8)
	s_waitcnt lgkmcnt(0)
	s_barrier
	v_mfma_f32_16x16x32_bf16 v[62:65], v[152:155], v[194:197], v[62:65]
	v_mfma_f32_16x16x32_bf16 v[62:65], v[162:165], v[198:201], v[62:65]
	v_mfma_f32_16x16x32_bf16 v[58:61], v[166:169], v[194:197], v[58:61]
	v_mfma_f32_16x16x32_bf16 v[58:61], v[170:173], v[198:201], v[58:61]
	v_mfma_f32_16x16x32_bf16 v[46:49], v[152:155], v[202:205], v[46:49]
	v_mfma_f32_16x16x32_bf16 v[46:49], v[162:165], v[206:209], v[46:49]
	v_mfma_f32_16x16x32_bf16 v[42:45], v[166:169], v[202:205], v[42:45]
	v_mfma_f32_16x16x32_bf16 v[42:45], v[170:173], v[206:209], v[42:45]
	v_mfma_f32_16x16x32_bf16 v[30:33], v[152:155], v[210:213], v[30:33]
	v_mfma_f32_16x16x32_bf16 v[30:33], v[162:165], v[214:217], v[30:33]
	v_mfma_f32_16x16x32_bf16 v[26:29], v[166:169], v[210:213], v[26:29]
	v_mfma_f32_16x16x32_bf16 v[26:29], v[170:173], v[214:217], v[26:29]
	v_mfma_f32_16x16x32_bf16 v[14:17], v[152:155], v[218:221], v[14:17]
	v_mfma_f32_16x16x32_bf16 v[14:17], v[162:165], v[222:225], v[14:17]
	v_mfma_f32_16x16x32_bf16 v[10:13], v[166:169], v[218:221], v[10:13]
	v_mfma_f32_16x16x32_bf16 v[10:13], v[170:173], v[222:225], v[10:13]
	v_mfma_f32_16x16x32_bf16 v[54:57], v[174:177], v[194:197], v[54:57]
	v_mfma_f32_16x16x32_bf16 v[54:57], v[182:185], v[198:201], v[54:57]
	v_mfma_f32_16x16x32_bf16 v[50:53], v[186:189], v[194:197], v[50:53]
	v_mfma_f32_16x16x32_bf16 v[50:53], v[190:193], v[198:201], v[50:53]
	v_mfma_f32_16x16x32_bf16 v[38:41], v[174:177], v[202:205], v[38:41]
	v_mfma_f32_16x16x32_bf16 v[38:41], v[182:185], v[206:209], v[38:41]
	v_mfma_f32_16x16x32_bf16 v[34:37], v[186:189], v[202:205], v[34:37]
	v_mfma_f32_16x16x32_bf16 v[34:37], v[190:193], v[206:209], v[34:37]
	v_mfma_f32_16x16x32_bf16 v[22:25], v[174:177], v[210:213], v[22:25]
	v_mfma_f32_16x16x32_bf16 v[22:25], v[182:185], v[214:217], v[22:25]
	v_mfma_f32_16x16x32_bf16 v[18:21], v[186:189], v[210:213], v[18:21]
	v_mfma_f32_16x16x32_bf16 v[18:21], v[190:193], v[214:217], v[18:21]
	v_mfma_f32_16x16x32_bf16 v[6:9], v[174:177], v[218:221], v[6:9]
	v_mfma_f32_16x16x32_bf16 v[6:9], v[182:185], v[222:225], v[6:9]
	v_mfma_f32_16x16x32_bf16 v[2:5], v[186:189], v[218:221], v[2:5]
	v_mfma_f32_16x16x32_bf16 v[2:5], v[190:193], v[222:225], v[2:5]
	s_barrier
	s_add_u32 s100, s16, 0x100000
	s_addc_u32 s101, s17, 0
	s_mov_b32 m0, s29
	ds_read_b128 v[152:155], v252 offset:32768
	ds_read_b128 v[162:165], v252 offset:33792
	global_load_lds_dwordx4 v146, s[100:101]
	s_mov_b32 m0, s36
	ds_read_b128 v[166:169], v252 offset:34816
	ds_read_b128 v[170:173], v252 offset:35840
	global_load_lds_dwordx4 v142, s[100:101]
	ds_read_b128 v[174:177], v252 offset:49152
	ds_read_b128 v[182:185], v252 offset:50176
	ds_read_b128 v[186:189], v252 offset:51200
	ds_read_b128 v[190:193], v252 offset:52224
	ds_read_b128 v[194:197], v161 offset:32768
	ds_read_b128 v[198:201], v161 offset:33792
	ds_read_b128 v[202:205], v161 offset:34816
	ds_read_b128 v[206:209], v161 offset:35840
	ds_read_b128 v[210:213], v161 offset:36864
	ds_read_b128 v[214:217], v161 offset:37888
	ds_read_b128 v[218:221], v161 offset:38912
	ds_read_b128 v[222:225], v161 offset:39936
	s_waitcnt vmcnt(8)
	s_waitcnt lgkmcnt(0)
	s_barrier
	v_mfma_f32_16x16x32_bf16 v[126:129], v[152:155], v[194:197], v[126:129]
	v_mfma_f32_16x16x32_bf16 v[126:129], v[162:165], v[198:201], v[126:129]
	v_mfma_f32_16x16x32_bf16 v[122:125], v[166:169], v[194:197], v[122:125]
	v_mfma_f32_16x16x32_bf16 v[122:125], v[170:173], v[198:201], v[122:125]
	v_mfma_f32_16x16x32_bf16 v[110:113], v[152:155], v[202:205], v[110:113]
	v_mfma_f32_16x16x32_bf16 v[110:113], v[162:165], v[206:209], v[110:113]
	v_mfma_f32_16x16x32_bf16 v[106:109], v[166:169], v[202:205], v[106:109]
	v_mfma_f32_16x16x32_bf16 v[106:109], v[170:173], v[206:209], v[106:109]
	v_mfma_f32_16x16x32_bf16 v[94:97], v[152:155], v[210:213], v[94:97]
	v_mfma_f32_16x16x32_bf16 v[94:97], v[162:165], v[214:217], v[94:97]
	v_mfma_f32_16x16x32_bf16 v[90:93], v[166:169], v[210:213], v[90:93]
	v_mfma_f32_16x16x32_bf16 v[90:93], v[170:173], v[214:217], v[90:93]
	v_mfma_f32_16x16x32_bf16 v[78:81], v[152:155], v[218:221], v[78:81]
	v_mfma_f32_16x16x32_bf16 v[78:81], v[162:165], v[222:225], v[78:81]
	v_mfma_f32_16x16x32_bf16 v[74:77], v[166:169], v[218:221], v[74:77]
	v_mfma_f32_16x16x32_bf16 v[74:77], v[170:173], v[222:225], v[74:77]
	v_mfma_f32_16x16x32_bf16 v[118:121], v[174:177], v[194:197], v[118:121]
	v_mfma_f32_16x16x32_bf16 v[118:121], v[182:185], v[198:201], v[118:121]
	v_mfma_f32_16x16x32_bf16 v[114:117], v[186:189], v[194:197], v[114:117]
	v_mfma_f32_16x16x32_bf16 v[114:117], v[190:193], v[198:201], v[114:117]
	v_mfma_f32_16x16x32_bf16 v[102:105], v[174:177], v[202:205], v[102:105]
	v_mfma_f32_16x16x32_bf16 v[102:105], v[182:185], v[206:209], v[102:105]
	v_mfma_f32_16x16x32_bf16 v[98:101], v[186:189], v[202:205], v[98:101]
	v_mfma_f32_16x16x32_bf16 v[98:101], v[190:193], v[206:209], v[98:101]
	v_mfma_f32_16x16x32_bf16 v[86:89], v[174:177], v[210:213], v[86:89]
	v_mfma_f32_16x16x32_bf16 v[86:89], v[182:185], v[214:217], v[86:89]
	v_mfma_f32_16x16x32_bf16 v[82:85], v[186:189], v[210:213], v[82:85]
	v_mfma_f32_16x16x32_bf16 v[82:85], v[190:193], v[214:217], v[82:85]
	v_mfma_f32_16x16x32_bf16 v[70:73], v[174:177], v[218:221], v[70:73]
	v_mfma_f32_16x16x32_bf16 v[70:73], v[182:185], v[222:225], v[70:73]
	v_mfma_f32_16x16x32_bf16 v[66:69], v[186:189], v[218:221], v[66:69]
	v_mfma_f32_16x16x32_bf16 v[66:69], v[190:193], v[222:225], v[66:69]
	s_barrier
	s_add_u32 s14, s14, 0x80
	s_addc_u32 s15, s15, 0
	s_add_i32 m0, s28, 0x18000
	ds_read_b128 v[194:197], v161 offset:49152
	ds_read_b128 v[198:201], v161 offset:50176
	global_load_lds_dwordx4 v144, s[14:15]
	s_add_i32 m0, s28, 0x1a000
	s_add_u32 s98, s98, 0x80
	s_addc_u32 s99, s99, 0
	ds_read_b128 v[202:205], v161 offset:51200
	global_load_lds_dwordx4 v140, s[14:15]
	s_add_i32 m0, s28, 0x1c000
	ds_read_b128 v[206:209], v161 offset:52224
	ds_read_b128 v[210:213], v161 offset:53248
	global_load_lds_dwordx4 v144, s[98:99]
	s_add_i32 m0, s28, 0x1e000
	s_add_u32 s16, s16, 0x80
	s_addc_u32 s17, s17, 0
	ds_read_b128 v[214:217], v161 offset:54272
	ds_read_b128 v[218:221], v161 offset:55296
	global_load_lds_dwordx4 v140, s[98:99]
	s_mov_b32 m0, s39
	ds_read_b128 v[222:225], v161 offset:56320
	global_load_lds_dwordx4 v146, s[16:17]
	s_mov_b32 m0, s44
	s_nop 0
	global_load_lds_dwordx4 v142, s[16:17]
	s_waitcnt vmcnt(8)
	s_waitcnt lgkmcnt(0)
	s_barrier
	v_mfma_f32_16x16x32_bf16 v[62:65], v[152:155], v[194:197], v[62:65]
	v_mfma_f32_16x16x32_bf16 v[62:65], v[162:165], v[198:201], v[62:65]
	v_mfma_f32_16x16x32_bf16 v[58:61], v[166:169], v[194:197], v[58:61]
	v_mfma_f32_16x16x32_bf16 v[58:61], v[170:173], v[198:201], v[58:61]
	v_mfma_f32_16x16x32_bf16 v[46:49], v[152:155], v[202:205], v[46:49]
	v_mfma_f32_16x16x32_bf16 v[46:49], v[162:165], v[206:209], v[46:49]
	v_mfma_f32_16x16x32_bf16 v[42:45], v[166:169], v[202:205], v[42:45]
	v_mfma_f32_16x16x32_bf16 v[42:45], v[170:173], v[206:209], v[42:45]
	v_mfma_f32_16x16x32_bf16 v[30:33], v[152:155], v[210:213], v[30:33]
	v_mfma_f32_16x16x32_bf16 v[30:33], v[162:165], v[214:217], v[30:33]
	v_mfma_f32_16x16x32_bf16 v[26:29], v[166:169], v[210:213], v[26:29]
	v_mfma_f32_16x16x32_bf16 v[26:29], v[170:173], v[214:217], v[26:29]
	v_mfma_f32_16x16x32_bf16 v[14:17], v[152:155], v[218:221], v[14:17]
	v_mfma_f32_16x16x32_bf16 v[14:17], v[162:165], v[222:225], v[14:17]
	v_mfma_f32_16x16x32_bf16 v[10:13], v[166:169], v[218:221], v[10:13]
	v_mfma_f32_16x16x32_bf16 v[10:13], v[170:173], v[222:225], v[10:13]
	v_mfma_f32_16x16x32_bf16 v[54:57], v[174:177], v[194:197], v[54:57]
	v_mfma_f32_16x16x32_bf16 v[54:57], v[182:185], v[198:201], v[54:57]
	v_mfma_f32_16x16x32_bf16 v[50:53], v[186:189], v[194:197], v[50:53]
	v_mfma_f32_16x16x32_bf16 v[50:53], v[190:193], v[198:201], v[50:53]
	v_mfma_f32_16x16x32_bf16 v[38:41], v[174:177], v[202:205], v[38:41]
	v_mfma_f32_16x16x32_bf16 v[38:41], v[182:185], v[206:209], v[38:41]
	v_mfma_f32_16x16x32_bf16 v[34:37], v[186:189], v[202:205], v[34:37]
	v_mfma_f32_16x16x32_bf16 v[34:37], v[190:193], v[206:209], v[34:37]
	v_mfma_f32_16x16x32_bf16 v[22:25], v[174:177], v[210:213], v[22:25]
	v_mfma_f32_16x16x32_bf16 v[22:25], v[182:185], v[214:217], v[22:25]
	v_mfma_f32_16x16x32_bf16 v[18:21], v[186:189], v[210:213], v[18:21]
	v_mfma_f32_16x16x32_bf16 v[18:21], v[190:193], v[214:217], v[18:21]
	v_mfma_f32_16x16x32_bf16 v[6:9], v[174:177], v[218:221], v[6:9]
	v_mfma_f32_16x16x32_bf16 v[6:9], v[182:185], v[222:225], v[6:9]
	v_mfma_f32_16x16x32_bf16 v[2:5], v[186:189], v[218:221], v[2:5]
	v_mfma_f32_16x16x32_bf16 v[2:5], v[190:193], v[222:225], v[2:5]
	s_barrier
	s_add_i32 s35, s35, 2
	s_add_u32 s12, s12, 0x100
	s_addc_u32 s13, s13, 0
	s_add_u32 s0, s0, 0x100
	s_addc_u32 s1, s1, 0
	s_cmp_gt_u32 s35, 61
	s_cbranch_scc0 .LBB0_572
	s_and_b64 vcc, exec, s[10:11]
	s_cbranch_vccz .LBB0_575
	s_barrier

.LBB0_881:
	v_add_u32_e32 v252, 0x10000, v155
	s_add_u32 s10, s10, 0x100080
	s_addc_u32 s11, s11, 0
	s_add_u32 s0, s38, 0x100
	v_mov_b32_e32 v4, 0
	s_addc_u32 s1, s39, 0
	s_mov_b32 s12, -2
	v_mov_b32_e32 v5, v4
	v_mov_b32_e32 v6, v4
	v_mov_b32_e32 v7, v4
	v_mov_b32_e32 v8, v4
	v_mov_b32_e32 v9, v4
	v_mov_b32_e32 v10, v4
	v_mov_b32_e32 v11, v4
	v_mov_b32_e32 v20, v4
	v_mov_b32_e32 v21, v4
	v_mov_b32_e32 v22, v4
	v_mov_b32_e32 v23, v4
	v_mov_b32_e32 v24, v4
	v_mov_b32_e32 v25, v4
	v_mov_b32_e32 v26, v4
	v_mov_b32_e32 v27, v4
	v_mov_b32_e32 v36, v4
	v_mov_b32_e32 v37, v4
	v_mov_b32_e32 v38, v4
	v_mov_b32_e32 v39, v4
	v_mov_b32_e32 v40, v4
	v_mov_b32_e32 v41, v4
	v_mov_b32_e32 v42, v4
	v_mov_b32_e32 v43, v4
	v_mov_b32_e32 v52, v4
	v_mov_b32_e32 v53, v4
	v_mov_b32_e32 v54, v4
	v_mov_b32_e32 v55, v4
	v_mov_b32_e32 v56, v4
	v_mov_b32_e32 v57, v4
	v_mov_b32_e32 v58, v4
	v_mov_b32_e32 v59, v4
	v_mov_b32_e32 v12, v4
	v_mov_b32_e32 v13, v4
	v_mov_b32_e32 v14, v4
	v_mov_b32_e32 v15, v4
	v_mov_b32_e32 v16, v4
	v_mov_b32_e32 v17, v4
	v_mov_b32_e32 v18, v4
	v_mov_b32_e32 v19, v4
	v_mov_b32_e32 v28, v4
	v_mov_b32_e32 v29, v4
	v_mov_b32_e32 v30, v4
	v_mov_b32_e32 v31, v4
	v_mov_b32_e32 v32, v4
	v_mov_b32_e32 v33, v4
	v_mov_b32_e32 v34, v4
	v_mov_b32_e32 v35, v4
	v_mov_b32_e32 v44, v4
	v_mov_b32_e32 v45, v4
	v_mov_b32_e32 v46, v4
	v_mov_b32_e32 v47, v4
	v_mov_b32_e32 v48, v4
	v_mov_b32_e32 v49, v4
	v_mov_b32_e32 v50, v4
	v_mov_b32_e32 v51, v4
	v_mov_b32_e32 v60, v4
	v_mov_b32_e32 v61, v4
	v_mov_b32_e32 v62, v4
	v_mov_b32_e32 v63, v4
	v_mov_b32_e32 v64, v4
	v_mov_b32_e32 v65, v4
	v_mov_b32_e32 v66, v4
	v_mov_b32_e32 v67, v4
	v_mov_b32_e32 v68, v4
	v_mov_b32_e32 v69, v4
	v_mov_b32_e32 v70, v4
	v_mov_b32_e32 v71, v4
	v_mov_b32_e32 v72, v4
	v_mov_b32_e32 v73, v4
	v_mov_b32_e32 v74, v4
	v_mov_b32_e32 v75, v4
	v_mov_b32_e32 v84, v4
	v_mov_b32_e32 v85, v4
	v_mov_b32_e32 v86, v4
	v_mov_b32_e32 v87, v4
	v_mov_b32_e32 v88, v4
	v_mov_b32_e32 v89, v4
	v_mov_b32_e32 v90, v4
	v_mov_b32_e32 v91, v4
	v_mov_b32_e32 v100, v4
	v_mov_b32_e32 v101, v4
	v_mov_b32_e32 v102, v4
	v_mov_b32_e32 v103, v4
	v_mov_b32_e32 v104, v4
	v_mov_b32_e32 v105, v4
	v_mov_b32_e32 v106, v4
	v_mov_b32_e32 v107, v4
	v_mov_b32_e32 v116, v4
	v_mov_b32_e32 v117, v4
	v_mov_b32_e32 v118, v4
	v_mov_b32_e32 v119, v4
	v_mov_b32_e32 v120, v4
	v_mov_b32_e32 v121, v4
	v_mov_b32_e32 v122, v4
	v_mov_b32_e32 v123, v4
	v_mov_b32_e32 v76, v4
	v_mov_b32_e32 v77, v4
	v_mov_b32_e32 v78, v4
	v_mov_b32_e32 v79, v4
	v_mov_b32_e32 v80, v4
	v_mov_b32_e32 v81, v4
	v_mov_b32_e32 v82, v4
	v_mov_b32_e32 v83, v4
	v_mov_b32_e32 v92, v4
	v_mov_b32_e32 v93, v4
	v_mov_b32_e32 v94, v4
	v_mov_b32_e32 v95, v4
	v_mov_b32_e32 v96, v4
	v_mov_b32_e32 v97, v4
	v_mov_b32_e32 v98, v4
	v_mov_b32_e32 v99, v4
	v_mov_b32_e32 v108, v4
	v_mov_b32_e32 v109, v4
	v_mov_b32_e32 v110, v4
	v_mov_b32_e32 v111, v4
	v_mov_b32_e32 v112, v4
	v_mov_b32_e32 v113, v4
	v_mov_b32_e32 v114, v4
	v_mov_b32_e32 v115, v4
	v_mov_b32_e32 v124, v4
	v_mov_b32_e32 v125, v4
	v_mov_b32_e32 v126, v4
	v_mov_b32_e32 v127, v4
	v_mov_b32_e32 v128, v4
	v_mov_b32_e32 v129, v4
	v_mov_b32_e32 v130, v4
	v_mov_b32_e32 v131, v4
.LBB0_882:
	s_add_u32 s20, s10, 0xfff00080
	s_addc_u32 s21, s11, -1
	s_cmp_eq_u32 s12, 60
	s_cselect_b32 s43, s55, s21
	s_cselect_b32 s42, s54, s20
	s_cselect_b32 s39, s37, s1
	s_cselect_b32 s38, s36, s0
	s_add_i32 m0, s29, 0xc000
	ds_read_b128 v[146:149], v252
	ds_read_b128 v[150:153], v252 offset:1024
	global_load_lds_dwordx4 v140, s[10:11]
	s_add_i32 m0, s29, 0xe000
	ds_read_b128 v[158:161], v252 offset:2048
	ds_read_b128 v[162:165], v252 offset:3072
	global_load_lds_dwordx4 v142, s[10:11]
	ds_read_b128 v[166:169], v252 offset:16384
	ds_read_b128 v[170:173], v252 offset:17408
	ds_read_b128 v[174:177], v252 offset:18432
	ds_read_b128 v[186:189], v252 offset:19456
	ds_read_b128 v[190:193], v157
	ds_read_b128 v[194:197], v157 offset:1024
	ds_read_b128 v[198:201], v157 offset:2048
	ds_read_b128 v[202:205], v157 offset:3072
	ds_read_b128 v[206:209], v157 offset:4096
	ds_read_b128 v[210:213], v157 offset:5120
	ds_read_b128 v[214:217], v157 offset:6144
	ds_read_b128 v[218:221], v157 offset:7168
	s_waitcnt vmcnt(8)
	s_waitcnt lgkmcnt(0)
	s_barrier
	v_mfma_f32_16x16x32_bf16 v[128:131], v[146:149], v[190:193], v[128:131]
	v_mfma_f32_16x16x32_bf16 v[128:131], v[150:153], v[194:197], v[128:131]
	v_mfma_f32_16x16x32_bf16 v[124:127], v[158:161], v[190:193], v[124:127]
	v_mfma_f32_16x16x32_bf16 v[124:127], v[162:165], v[194:197], v[124:127]
	v_mfma_f32_16x16x32_bf16 v[112:115], v[146:149], v[198:201], v[112:115]
	v_mfma_f32_16x16x32_bf16 v[112:115], v[150:153], v[202:205], v[112:115]
	v_mfma_f32_16x16x32_bf16 v[108:111], v[158:161], v[198:201], v[108:111]
	v_mfma_f32_16x16x32_bf16 v[108:111], v[162:165], v[202:205], v[108:111]
	v_mfma_f32_16x16x32_bf16 v[96:99], v[146:149], v[206:209], v[96:99]
	v_mfma_f32_16x16x32_bf16 v[96:99], v[150:153], v[210:213], v[96:99]
	v_mfma_f32_16x16x32_bf16 v[92:95], v[158:161], v[206:209], v[92:95]
	v_mfma_f32_16x16x32_bf16 v[92:95], v[162:165], v[210:213], v[92:95]
	v_mfma_f32_16x16x32_bf16 v[80:83], v[146:149], v[214:217], v[80:83]
	v_mfma_f32_16x16x32_bf16 v[80:83], v[150:153], v[218:221], v[80:83]
	v_mfma_f32_16x16x32_bf16 v[76:79], v[158:161], v[214:217], v[76:79]
	v_mfma_f32_16x16x32_bf16 v[76:79], v[162:165], v[218:221], v[76:79]
	v_mfma_f32_16x16x32_bf16 v[120:123], v[166:169], v[190:193], v[120:123]
	v_mfma_f32_16x16x32_bf16 v[120:123], v[170:173], v[194:197], v[120:123]
	v_mfma_f32_16x16x32_bf16 v[116:119], v[174:177], v[190:193], v[116:119]
	v_mfma_f32_16x16x32_bf16 v[116:119], v[186:189], v[194:197], v[116:119]
	v_mfma_f32_16x16x32_bf16 v[104:107], v[166:169], v[198:201], v[104:107]
	v_mfma_f32_16x16x32_bf16 v[104:107], v[170:173], v[202:205], v[104:107]
	v_mfma_f32_16x16x32_bf16 v[100:103], v[174:177], v[198:201], v[100:103]
	v_mfma_f32_16x16x32_bf16 v[100:103], v[186:189], v[202:205], v[100:103]
	v_mfma_f32_16x16x32_bf16 v[88:91], v[166:169], v[206:209], v[88:91]
	v_mfma_f32_16x16x32_bf16 v[88:91], v[170:173], v[210:213], v[88:91]
	v_mfma_f32_16x16x32_bf16 v[84:87], v[174:177], v[206:209], v[84:87]
	v_mfma_f32_16x16x32_bf16 v[84:87], v[186:189], v[210:213], v[84:87]
	v_mfma_f32_16x16x32_bf16 v[72:75], v[166:169], v[214:217], v[72:75]
	v_mfma_f32_16x16x32_bf16 v[72:75], v[170:173], v[218:221], v[72:75]
	v_mfma_f32_16x16x32_bf16 v[68:71], v[174:177], v[214:217], v[68:71]
	v_mfma_f32_16x16x32_bf16 v[68:71], v[186:189], v[218:221], v[68:71]
	s_barrier
	s_add_i32 m0, s58, 0x10000
	ds_read_b128 v[190:193], v157 offset:16384
	ds_read_b128 v[194:197], v157 offset:17408
	global_load_lds_dwordx4 v134, s[38:39]
	s_add_i32 m0, s58, 0x12000
	s_add_u32 s98, s38, 0x100000
	s_addc_u32 s99, s39, 0
	ds_read_b128 v[198:201], v157 offset:18432
	global_load_lds_dwordx4 v138, s[38:39]
	s_add_i32 m0, s58, 0x14000
	ds_read_b128 v[202:205], v157 offset:19456
	ds_read_b128 v[206:209], v157 offset:20480
	global_load_lds_dwordx4 v134, s[98:99]
	s_add_i32 m0, s58, 0x16000
	ds_read_b128 v[210:213], v157 offset:21504
	ds_read_b128 v[214:217], v157 offset:22528
	global_load_lds_dwordx4 v138, s[98:99]
	s_mov_b32 m0, s29
	ds_read_b128 v[218:221], v157 offset:23552
	global_load_lds_dwordx4 v132, s[42:43]
	s_mov_b32 m0, s31
	s_nop 0
	global_load_lds_dwordx4 v136, s[42:43]
	s_waitcnt vmcnt(8)
	s_waitcnt lgkmcnt(0)
	s_barrier
	v_mfma_f32_16x16x32_bf16 v[64:67], v[146:149], v[190:193], v[64:67]
	v_mfma_f32_16x16x32_bf16 v[64:67], v[150:153], v[194:197], v[64:67]
	v_mfma_f32_16x16x32_bf16 v[60:63], v[158:161], v[190:193], v[60:63]
	v_mfma_f32_16x16x32_bf16 v[60:63], v[162:165], v[194:197], v[60:63]
	v_mfma_f32_16x16x32_bf16 v[48:51], v[146:149], v[198:201], v[48:51]
	v_mfma_f32_16x16x32_bf16 v[48:51], v[150:153], v[202:205], v[48:51]
	v_mfma_f32_16x16x32_bf16 v[44:47], v[158:161], v[198:201], v[44:47]
	v_mfma_f32_16x16x32_bf16 v[44:47], v[162:165], v[202:205], v[44:47]
	v_mfma_f32_16x16x32_bf16 v[32:35], v[146:149], v[206:209], v[32:35]
	v_mfma_f32_16x16x32_bf16 v[32:35], v[150:153], v[210:213], v[32:35]
	v_mfma_f32_16x16x32_bf16 v[28:31], v[158:161], v[206:209], v[28:31]
	v_mfma_f32_16x16x32_bf16 v[28:31], v[162:165], v[210:213], v[28:31]
	v_mfma_f32_16x16x32_bf16 v[16:19], v[146:149], v[214:217], v[16:19]
	v_mfma_f32_16x16x32_bf16 v[16:19], v[150:153], v[218:221], v[16:19]
	v_mfma_f32_16x16x32_bf16 v[12:15], v[158:161], v[214:217], v[12:15]
	v_mfma_f32_16x16x32_bf16 v[12:15], v[162:165], v[218:221], v[12:15]
	v_mfma_f32_16x16x32_bf16 v[56:59], v[166:169], v[190:193], v[56:59]
	v_mfma_f32_16x16x32_bf16 v[56:59], v[170:173], v[194:197], v[56:59]
	v_mfma_f32_16x16x32_bf16 v[52:55], v[174:177], v[190:193], v[52:55]
	v_mfma_f32_16x16x32_bf16 v[52:55], v[186:189], v[194:197], v[52:55]
	v_mfma_f32_16x16x32_bf16 v[40:43], v[166:169], v[198:201], v[40:43]
	v_mfma_f32_16x16x32_bf16 v[40:43], v[170:173], v[202:205], v[40:43]
	v_mfma_f32_16x16x32_bf16 v[36:39], v[174:177], v[198:201], v[36:39]
	v_mfma_f32_16x16x32_bf16 v[36:39], v[186:189], v[202:205], v[36:39]
	v_mfma_f32_16x16x32_bf16 v[24:27], v[166:169], v[206:209], v[24:27]
	v_mfma_f32_16x16x32_bf16 v[24:27], v[170:173], v[210:213], v[24:27]
	v_mfma_f32_16x16x32_bf16 v[20:23], v[174:177], v[206:209], v[20:23]
	v_mfma_f32_16x16x32_bf16 v[20:23], v[186:189], v[210:213], v[20:23]
	v_mfma_f32_16x16x32_bf16 v[8:11], v[166:169], v[214:217], v[8:11]
	v_mfma_f32_16x16x32_bf16 v[8:11], v[170:173], v[218:221], v[8:11]
	v_mfma_f32_16x16x32_bf16 v[4:7], v[174:177], v[214:217], v[4:7]
	v_mfma_f32_16x16x32_bf16 v[4:7], v[186:189], v[218:221], v[4:7]
	s_barrier
	s_add_u32 s100, s42, 0x100000
	s_addc_u32 s101, s43, 0
	s_mov_b32 m0, s59
	ds_read_b128 v[146:149], v252 offset:32768
	ds_read_b128 v[150:153], v252 offset:33792
	global_load_lds_dwordx4 v132, s[100:101]
	s_mov_b32 m0, s94
	ds_read_b128 v[158:161], v252 offset:34816
	ds_read_b128 v[162:165], v252 offset:35840
	global_load_lds_dwordx4 v136, s[100:101]
	ds_read_b128 v[166:169], v252 offset:49152
	ds_read_b128 v[170:173], v252 offset:50176
	ds_read_b128 v[174:177], v252 offset:51200
	ds_read_b128 v[186:189], v252 offset:52224
	ds_read_b128 v[190:193], v157 offset:32768
	ds_read_b128 v[194:197], v157 offset:33792
	ds_read_b128 v[198:201], v157 offset:34816
	ds_read_b128 v[202:205], v157 offset:35840
	ds_read_b128 v[206:209], v157 offset:36864
	ds_read_b128 v[210:213], v157 offset:37888
	ds_read_b128 v[214:217], v157 offset:38912
	ds_read_b128 v[218:221], v157 offset:39936
	s_waitcnt vmcnt(8)
	s_waitcnt lgkmcnt(0)
	s_barrier
	v_mfma_f32_16x16x32_bf16 v[128:131], v[146:149], v[190:193], v[128:131]
	v_mfma_f32_16x16x32_bf16 v[128:131], v[150:153], v[194:197], v[128:131]
	v_mfma_f32_16x16x32_bf16 v[124:127], v[158:161], v[190:193], v[124:127]
	v_mfma_f32_16x16x32_bf16 v[124:127], v[162:165], v[194:197], v[124:127]
	v_mfma_f32_16x16x32_bf16 v[112:115], v[146:149], v[198:201], v[112:115]
	v_mfma_f32_16x16x32_bf16 v[112:115], v[150:153], v[202:205], v[112:115]
	v_mfma_f32_16x16x32_bf16 v[108:111], v[158:161], v[198:201], v[108:111]
	v_mfma_f32_16x16x32_bf16 v[108:111], v[162:165], v[202:205], v[108:111]
	v_mfma_f32_16x16x32_bf16 v[96:99], v[146:149], v[206:209], v[96:99]
	v_mfma_f32_16x16x32_bf16 v[96:99], v[150:153], v[210:213], v[96:99]
	v_mfma_f32_16x16x32_bf16 v[92:95], v[158:161], v[206:209], v[92:95]
	v_mfma_f32_16x16x32_bf16 v[92:95], v[162:165], v[210:213], v[92:95]
	v_mfma_f32_16x16x32_bf16 v[80:83], v[146:149], v[214:217], v[80:83]
	v_mfma_f32_16x16x32_bf16 v[80:83], v[150:153], v[218:221], v[80:83]
	v_mfma_f32_16x16x32_bf16 v[76:79], v[158:161], v[214:217], v[76:79]
	v_mfma_f32_16x16x32_bf16 v[76:79], v[162:165], v[218:221], v[76:79]
	v_mfma_f32_16x16x32_bf16 v[120:123], v[166:169], v[190:193], v[120:123]
	v_mfma_f32_16x16x32_bf16 v[120:123], v[170:173], v[194:197], v[120:123]
	v_mfma_f32_16x16x32_bf16 v[116:119], v[174:177], v[190:193], v[116:119]
	v_mfma_f32_16x16x32_bf16 v[116:119], v[186:189], v[194:197], v[116:119]
	v_mfma_f32_16x16x32_bf16 v[104:107], v[166:169], v[198:201], v[104:107]
	v_mfma_f32_16x16x32_bf16 v[104:107], v[170:173], v[202:205], v[104:107]
	v_mfma_f32_16x16x32_bf16 v[100:103], v[174:177], v[198:201], v[100:103]
	v_mfma_f32_16x16x32_bf16 v[100:103], v[186:189], v[202:205], v[100:103]
	v_mfma_f32_16x16x32_bf16 v[88:91], v[166:169], v[206:209], v[88:91]
	v_mfma_f32_16x16x32_bf16 v[88:91], v[170:173], v[210:213], v[88:91]
	v_mfma_f32_16x16x32_bf16 v[84:87], v[174:177], v[206:209], v[84:87]
	v_mfma_f32_16x16x32_bf16 v[84:87], v[186:189], v[210:213], v[84:87]
	v_mfma_f32_16x16x32_bf16 v[72:75], v[166:169], v[214:217], v[72:75]
	v_mfma_f32_16x16x32_bf16 v[72:75], v[170:173], v[218:221], v[72:75]
	v_mfma_f32_16x16x32_bf16 v[68:71], v[174:177], v[214:217], v[68:71]
	v_mfma_f32_16x16x32_bf16 v[68:71], v[186:189], v[218:221], v[68:71]
	s_barrier
	s_add_u32 s38, s38, 0x80
	s_addc_u32 s39, s39, 0
	s_add_i32 m0, s58, 0x18000
	ds_read_b128 v[190:193], v157 offset:49152
	ds_read_b128 v[194:197], v157 offset:50176
	global_load_lds_dwordx4 v134, s[38:39]
	s_add_i32 m0, s58, 0x1a000
	s_add_u32 s98, s98, 0x80
	s_addc_u32 s99, s99, 0
	ds_read_b128 v[198:201], v157 offset:51200
	global_load_lds_dwordx4 v138, s[38:39]
	s_add_i32 m0, s58, 0x1c000
	ds_read_b128 v[202:205], v157 offset:52224
	ds_read_b128 v[206:209], v157 offset:53248
	global_load_lds_dwordx4 v134, s[98:99]
	s_add_i32 m0, s58, 0x1e000
	s_add_u32 s42, s42, 0x80
	s_addc_u32 s43, s43, 0
	ds_read_b128 v[210:213], v157 offset:54272
	ds_read_b128 v[214:217], v157 offset:55296
	global_load_lds_dwordx4 v138, s[98:99]
	s_mov_b32 m0, s14
	ds_read_b128 v[218:221], v157 offset:56320
	global_load_lds_dwordx4 v132, s[42:43]
	s_mov_b32 m0, s15
	s_nop 0
	global_load_lds_dwordx4 v136, s[42:43]
	s_waitcnt vmcnt(8)
	s_waitcnt lgkmcnt(0)
	s_barrier
	v_mfma_f32_16x16x32_bf16 v[64:67], v[146:149], v[190:193], v[64:67]
	v_mfma_f32_16x16x32_bf16 v[64:67], v[150:153], v[194:197], v[64:67]
	v_mfma_f32_16x16x32_bf16 v[60:63], v[158:161], v[190:193], v[60:63]
	v_mfma_f32_16x16x32_bf16 v[60:63], v[162:165], v[194:197], v[60:63]
	v_mfma_f32_16x16x32_bf16 v[48:51], v[146:149], v[198:201], v[48:51]
	v_mfma_f32_16x16x32_bf16 v[48:51], v[150:153], v[202:205], v[48:51]
	v_mfma_f32_16x16x32_bf16 v[44:47], v[158:161], v[198:201], v[44:47]
	v_mfma_f32_16x16x32_bf16 v[44:47], v[162:165], v[202:205], v[44:47]
	v_mfma_f32_16x16x32_bf16 v[32:35], v[146:149], v[206:209], v[32:35]
	v_mfma_f32_16x16x32_bf16 v[32:35], v[150:153], v[210:213], v[32:35]
	v_mfma_f32_16x16x32_bf16 v[28:31], v[158:161], v[206:209], v[28:31]
	v_mfma_f32_16x16x32_bf16 v[28:31], v[162:165], v[210:213], v[28:31]
	v_mfma_f32_16x16x32_bf16 v[16:19], v[146:149], v[214:217], v[16:19]
	v_mfma_f32_16x16x32_bf16 v[16:19], v[150:153], v[218:221], v[16:19]
	v_mfma_f32_16x16x32_bf16 v[12:15], v[158:161], v[214:217], v[12:15]
	v_mfma_f32_16x16x32_bf16 v[12:15], v[162:165], v[218:221], v[12:15]
	v_mfma_f32_16x16x32_bf16 v[56:59], v[166:169], v[190:193], v[56:59]
	v_mfma_f32_16x16x32_bf16 v[56:59], v[170:173], v[194:197], v[56:59]
	v_mfma_f32_16x16x32_bf16 v[52:55], v[174:177], v[190:193], v[52:55]
	v_mfma_f32_16x16x32_bf16 v[52:55], v[186:189], v[194:197], v[52:55]
	v_mfma_f32_16x16x32_bf16 v[40:43], v[166:169], v[198:201], v[40:43]
	v_mfma_f32_16x16x32_bf16 v[40:43], v[170:173], v[202:205], v[40:43]
	v_mfma_f32_16x16x32_bf16 v[36:39], v[174:177], v[198:201], v[36:39]
	v_mfma_f32_16x16x32_bf16 v[36:39], v[186:189], v[202:205], v[36:39]
	v_mfma_f32_16x16x32_bf16 v[24:27], v[166:169], v[206:209], v[24:27]
	v_mfma_f32_16x16x32_bf16 v[24:27], v[170:173], v[210:213], v[24:27]
	v_mfma_f32_16x16x32_bf16 v[20:23], v[174:177], v[206:209], v[20:23]
	v_mfma_f32_16x16x32_bf16 v[20:23], v[186:189], v[210:213], v[20:23]
	v_mfma_f32_16x16x32_bf16 v[8:11], v[166:169], v[214:217], v[8:11]
	v_mfma_f32_16x16x32_bf16 v[8:11], v[170:173], v[218:221], v[8:11]
	v_mfma_f32_16x16x32_bf16 v[4:7], v[174:177], v[214:217], v[4:7]
	v_mfma_f32_16x16x32_bf16 v[4:7], v[186:189], v[218:221], v[4:7]
	s_barrier
	s_add_i32 s12, s12, 2
	s_add_u32 s10, s10, 0x100
	s_addc_u32 s11, s11, 0
	s_add_u32 s0, s0, 0x100
	s_addc_u32 s1, s1, 0
	s_cmp_gt_u32 s12, 61
	s_cbranch_scc0 .LBB0_882
	s_and_b64 vcc, exec, s[48:49]
	s_cbranch_vccz .LBB0_885
	s_barrier

.LBB0_1225:
	v_add_u32_e32 v252, 0x10000, v151
	s_add_u32 s10, s10, 0x100080
	s_addc_u32 s11, s11, 0
	s_add_u32 s0, s28, 0x100
	v_mov_b32_e32 v4, 0
	s_addc_u32 s1, s29, 0
	s_mov_b32 s20, -2
	v_mov_b32_e32 v5, v4
	v_mov_b32_e32 v6, v4
	v_mov_b32_e32 v7, v4
	v_mov_b32_e32 v8, v4
	v_mov_b32_e32 v9, v4
	v_mov_b32_e32 v10, v4
	v_mov_b32_e32 v11, v4
	v_mov_b32_e32 v20, v4
	v_mov_b32_e32 v21, v4
	v_mov_b32_e32 v22, v4
	v_mov_b32_e32 v23, v4
	v_mov_b32_e32 v24, v4
	v_mov_b32_e32 v25, v4
	v_mov_b32_e32 v26, v4
	v_mov_b32_e32 v27, v4
	v_mov_b32_e32 v36, v4
	v_mov_b32_e32 v37, v4
	v_mov_b32_e32 v38, v4
	v_mov_b32_e32 v39, v4
	v_mov_b32_e32 v40, v4
	v_mov_b32_e32 v41, v4
	v_mov_b32_e32 v42, v4
	v_mov_b32_e32 v43, v4
	v_mov_b32_e32 v52, v4
	v_mov_b32_e32 v53, v4
	v_mov_b32_e32 v54, v4
	v_mov_b32_e32 v55, v4
	v_mov_b32_e32 v56, v4
	v_mov_b32_e32 v57, v4
	v_mov_b32_e32 v58, v4
	v_mov_b32_e32 v59, v4
	v_mov_b32_e32 v12, v4
	v_mov_b32_e32 v13, v4
	v_mov_b32_e32 v14, v4
	v_mov_b32_e32 v15, v4
	v_mov_b32_e32 v16, v4
	v_mov_b32_e32 v17, v4
	v_mov_b32_e32 v18, v4
	v_mov_b32_e32 v19, v4
	v_mov_b32_e32 v28, v4
	v_mov_b32_e32 v29, v4
	v_mov_b32_e32 v30, v4
	v_mov_b32_e32 v31, v4
	v_mov_b32_e32 v32, v4
	v_mov_b32_e32 v33, v4
	v_mov_b32_e32 v34, v4
	v_mov_b32_e32 v35, v4
	v_mov_b32_e32 v44, v4
	v_mov_b32_e32 v45, v4
	v_mov_b32_e32 v46, v4
	v_mov_b32_e32 v47, v4
	v_mov_b32_e32 v48, v4
	v_mov_b32_e32 v49, v4
	v_mov_b32_e32 v50, v4
	v_mov_b32_e32 v51, v4
	v_mov_b32_e32 v60, v4
	v_mov_b32_e32 v61, v4
	v_mov_b32_e32 v62, v4
	v_mov_b32_e32 v63, v4
	v_mov_b32_e32 v64, v4
	v_mov_b32_e32 v65, v4
	v_mov_b32_e32 v66, v4
	v_mov_b32_e32 v67, v4
	v_mov_b32_e32 v68, v4
	v_mov_b32_e32 v69, v4
	v_mov_b32_e32 v70, v4
	v_mov_b32_e32 v71, v4
	v_mov_b32_e32 v72, v4
	v_mov_b32_e32 v73, v4
	v_mov_b32_e32 v74, v4
	v_mov_b32_e32 v75, v4
	v_mov_b32_e32 v84, v4
	v_mov_b32_e32 v85, v4
	v_mov_b32_e32 v86, v4
	v_mov_b32_e32 v87, v4
	v_mov_b32_e32 v88, v4
	v_mov_b32_e32 v89, v4
	v_mov_b32_e32 v90, v4
	v_mov_b32_e32 v91, v4
	v_mov_b32_e32 v100, v4
	v_mov_b32_e32 v101, v4
	v_mov_b32_e32 v102, v4
	v_mov_b32_e32 v103, v4
	v_mov_b32_e32 v104, v4
	v_mov_b32_e32 v105, v4
	v_mov_b32_e32 v106, v4
	v_mov_b32_e32 v107, v4
	v_mov_b32_e32 v116, v4
	v_mov_b32_e32 v117, v4
	v_mov_b32_e32 v118, v4
	v_mov_b32_e32 v119, v4
	v_mov_b32_e32 v120, v4
	v_mov_b32_e32 v121, v4
	v_mov_b32_e32 v122, v4
	v_mov_b32_e32 v123, v4
	v_mov_b32_e32 v76, v4
	v_mov_b32_e32 v77, v4
	v_mov_b32_e32 v78, v4
	v_mov_b32_e32 v79, v4
	v_mov_b32_e32 v80, v4
	v_mov_b32_e32 v81, v4
	v_mov_b32_e32 v82, v4
	v_mov_b32_e32 v83, v4
	v_mov_b32_e32 v92, v4
	v_mov_b32_e32 v93, v4
	v_mov_b32_e32 v94, v4
	v_mov_b32_e32 v95, v4
	v_mov_b32_e32 v96, v4
	v_mov_b32_e32 v97, v4
	v_mov_b32_e32 v98, v4
	v_mov_b32_e32 v99, v4
	v_mov_b32_e32 v108, v4
	v_mov_b32_e32 v109, v4
	v_mov_b32_e32 v110, v4
	v_mov_b32_e32 v111, v4
	v_mov_b32_e32 v112, v4
	v_mov_b32_e32 v113, v4
	v_mov_b32_e32 v114, v4
	v_mov_b32_e32 v115, v4
	v_mov_b32_e32 v124, v4
	v_mov_b32_e32 v125, v4
	v_mov_b32_e32 v126, v4
	v_mov_b32_e32 v127, v4
	v_mov_b32_e32 v128, v4
	v_mov_b32_e32 v129, v4
	v_mov_b32_e32 v130, v4
	v_mov_b32_e32 v131, v4
.LBB0_1226:
	s_add_u32 s21, s10, 0xfff00080
	s_addc_u32 s22, s11, -1
	s_cmp_eq_u32 s20, 60
	s_cselect_b32 s31, s53, s22
	s_cselect_b32 s30, s52, s21
	s_cselect_b32 s29, s55, s1
	s_cselect_b32 s28, s54, s0
	s_add_i32 m0, s8, 0xc000
	ds_read_b128 v[144:147], v252
	ds_read_b128 v[154:157], v252 offset:1024
	global_load_lds_dwordx4 v140, s[10:11]
	s_add_i32 m0, s8, 0xe000
	ds_read_b128 v[158:161], v252 offset:2048
	ds_read_b128 v[162:165], v252 offset:3072
	global_load_lds_dwordx4 v142, s[10:11]
	ds_read_b128 v[166:169], v252 offset:16384
	ds_read_b128 v[170:173], v252 offset:17408
	ds_read_b128 v[174:177], v252 offset:18432
	ds_read_b128 v[186:189], v252 offset:19456
	ds_read_b128 v[190:193], v153
	ds_read_b128 v[194:197], v153 offset:1024
	ds_read_b128 v[198:201], v153 offset:2048
	ds_read_b128 v[202:205], v153 offset:3072
	ds_read_b128 v[206:209], v153 offset:4096
	ds_read_b128 v[210:213], v153 offset:5120
	ds_read_b128 v[214:217], v153 offset:6144
	ds_read_b128 v[218:221], v153 offset:7168
	s_waitcnt vmcnt(8)
	s_waitcnt lgkmcnt(0)
	s_barrier
	v_mfma_f32_16x16x32_bf16 v[128:131], v[144:147], v[190:193], v[128:131]
	v_mfma_f32_16x16x32_bf16 v[128:131], v[154:157], v[194:197], v[128:131]
	v_mfma_f32_16x16x32_bf16 v[124:127], v[158:161], v[190:193], v[124:127]
	v_mfma_f32_16x16x32_bf16 v[124:127], v[162:165], v[194:197], v[124:127]
	v_mfma_f32_16x16x32_bf16 v[112:115], v[144:147], v[198:201], v[112:115]
	v_mfma_f32_16x16x32_bf16 v[112:115], v[154:157], v[202:205], v[112:115]
	v_mfma_f32_16x16x32_bf16 v[108:111], v[158:161], v[198:201], v[108:111]
	v_mfma_f32_16x16x32_bf16 v[108:111], v[162:165], v[202:205], v[108:111]
	v_mfma_f32_16x16x32_bf16 v[96:99], v[144:147], v[206:209], v[96:99]
	v_mfma_f32_16x16x32_bf16 v[96:99], v[154:157], v[210:213], v[96:99]
	v_mfma_f32_16x16x32_bf16 v[92:95], v[158:161], v[206:209], v[92:95]
	v_mfma_f32_16x16x32_bf16 v[92:95], v[162:165], v[210:213], v[92:95]
	v_mfma_f32_16x16x32_bf16 v[80:83], v[144:147], v[214:217], v[80:83]
	v_mfma_f32_16x16x32_bf16 v[80:83], v[154:157], v[218:221], v[80:83]
	v_mfma_f32_16x16x32_bf16 v[76:79], v[158:161], v[214:217], v[76:79]
	v_mfma_f32_16x16x32_bf16 v[76:79], v[162:165], v[218:221], v[76:79]
	v_mfma_f32_16x16x32_bf16 v[120:123], v[166:169], v[190:193], v[120:123]
	v_mfma_f32_16x16x32_bf16 v[120:123], v[170:173], v[194:197], v[120:123]
	v_mfma_f32_16x16x32_bf16 v[116:119], v[174:177], v[190:193], v[116:119]
	v_mfma_f32_16x16x32_bf16 v[116:119], v[186:189], v[194:197], v[116:119]
	v_mfma_f32_16x16x32_bf16 v[104:107], v[166:169], v[198:201], v[104:107]
	v_mfma_f32_16x16x32_bf16 v[104:107], v[170:173], v[202:205], v[104:107]
	v_mfma_f32_16x16x32_bf16 v[100:103], v[174:177], v[198:201], v[100:103]
	v_mfma_f32_16x16x32_bf16 v[100:103], v[186:189], v[202:205], v[100:103]
	v_mfma_f32_16x16x32_bf16 v[88:91], v[166:169], v[206:209], v[88:91]
	v_mfma_f32_16x16x32_bf16 v[88:91], v[170:173], v[210:213], v[88:91]
	v_mfma_f32_16x16x32_bf16 v[84:87], v[174:177], v[206:209], v[84:87]
	v_mfma_f32_16x16x32_bf16 v[84:87], v[186:189], v[210:213], v[84:87]
	v_mfma_f32_16x16x32_bf16 v[72:75], v[166:169], v[214:217], v[72:75]
	v_mfma_f32_16x16x32_bf16 v[72:75], v[170:173], v[218:221], v[72:75]
	v_mfma_f32_16x16x32_bf16 v[68:71], v[174:177], v[214:217], v[68:71]
	v_mfma_f32_16x16x32_bf16 v[68:71], v[186:189], v[218:221], v[68:71]
	s_barrier
	s_add_i32 m0, s38, 0x10000
	ds_read_b128 v[190:193], v153 offset:16384
	ds_read_b128 v[194:197], v153 offset:17408
	global_load_lds_dwordx4 v136, s[28:29]
	s_add_i32 m0, s38, 0x12000
	s_add_u32 s98, s28, 0x100000
	s_addc_u32 s99, s29, 0
	ds_read_b128 v[198:201], v153 offset:18432
	global_load_lds_dwordx4 v132, s[28:29]
	s_add_i32 m0, s38, 0x14000
	ds_read_b128 v[202:205], v153 offset:19456
	ds_read_b128 v[206:209], v153 offset:20480
	global_load_lds_dwordx4 v136, s[98:99]
	s_add_i32 m0, s38, 0x16000
	ds_read_b128 v[210:213], v153 offset:21504
	ds_read_b128 v[214:217], v153 offset:22528
	global_load_lds_dwordx4 v132, s[98:99]
	s_mov_b32 m0, s8
	ds_read_b128 v[218:221], v153 offset:23552
	global_load_lds_dwordx4 v138, s[30:31]
	s_mov_b32 m0, s9
	s_nop 0
	global_load_lds_dwordx4 v134, s[30:31]
	s_waitcnt vmcnt(8)
	s_waitcnt lgkmcnt(0)
	s_barrier
	v_mfma_f32_16x16x32_bf16 v[64:67], v[144:147], v[190:193], v[64:67]
	v_mfma_f32_16x16x32_bf16 v[64:67], v[154:157], v[194:197], v[64:67]
	v_mfma_f32_16x16x32_bf16 v[60:63], v[158:161], v[190:193], v[60:63]
	v_mfma_f32_16x16x32_bf16 v[60:63], v[162:165], v[194:197], v[60:63]
	v_mfma_f32_16x16x32_bf16 v[48:51], v[144:147], v[198:201], v[48:51]
	v_mfma_f32_16x16x32_bf16 v[48:51], v[154:157], v[202:205], v[48:51]
	v_mfma_f32_16x16x32_bf16 v[44:47], v[158:161], v[198:201], v[44:47]
	v_mfma_f32_16x16x32_bf16 v[44:47], v[162:165], v[202:205], v[44:47]
	v_mfma_f32_16x16x32_bf16 v[32:35], v[144:147], v[206:209], v[32:35]
	v_mfma_f32_16x16x32_bf16 v[32:35], v[154:157], v[210:213], v[32:35]
	v_mfma_f32_16x16x32_bf16 v[28:31], v[158:161], v[206:209], v[28:31]
	v_mfma_f32_16x16x32_bf16 v[28:31], v[162:165], v[210:213], v[28:31]
	v_mfma_f32_16x16x32_bf16 v[16:19], v[144:147], v[214:217], v[16:19]
	v_mfma_f32_16x16x32_bf16 v[16:19], v[154:157], v[218:221], v[16:19]
	v_mfma_f32_16x16x32_bf16 v[12:15], v[158:161], v[214:217], v[12:15]
	v_mfma_f32_16x16x32_bf16 v[12:15], v[162:165], v[218:221], v[12:15]
	v_mfma_f32_16x16x32_bf16 v[56:59], v[166:169], v[190:193], v[56:59]
	v_mfma_f32_16x16x32_bf16 v[56:59], v[170:173], v[194:197], v[56:59]
	v_mfma_f32_16x16x32_bf16 v[52:55], v[174:177], v[190:193], v[52:55]
	v_mfma_f32_16x16x32_bf16 v[52:55], v[186:189], v[194:197], v[52:55]
	v_mfma_f32_16x16x32_bf16 v[40:43], v[166:169], v[198:201], v[40:43]
	v_mfma_f32_16x16x32_bf16 v[40:43], v[170:173], v[202:205], v[40:43]
	v_mfma_f32_16x16x32_bf16 v[36:39], v[174:177], v[198:201], v[36:39]
	v_mfma_f32_16x16x32_bf16 v[36:39], v[186:189], v[202:205], v[36:39]
	v_mfma_f32_16x16x32_bf16 v[24:27], v[166:169], v[206:209], v[24:27]
	v_mfma_f32_16x16x32_bf16 v[24:27], v[170:173], v[210:213], v[24:27]
	v_mfma_f32_16x16x32_bf16 v[20:23], v[174:177], v[206:209], v[20:23]
	v_mfma_f32_16x16x32_bf16 v[20:23], v[186:189], v[210:213], v[20:23]
	v_mfma_f32_16x16x32_bf16 v[8:11], v[166:169], v[214:217], v[8:11]
	v_mfma_f32_16x16x32_bf16 v[8:11], v[170:173], v[218:221], v[8:11]
	v_mfma_f32_16x16x32_bf16 v[4:7], v[174:177], v[214:217], v[4:7]
	v_mfma_f32_16x16x32_bf16 v[4:7], v[186:189], v[218:221], v[4:7]
	s_barrier
	s_add_u32 s100, s30, 0x100000
	s_addc_u32 s101, s31, 0
	s_mov_b32 m0, s16
	ds_read_b128 v[144:147], v252 offset:32768
	ds_read_b128 v[154:157], v252 offset:33792
	global_load_lds_dwordx4 v138, s[100:101]
	s_mov_b32 m0, s17
	ds_read_b128 v[158:161], v252 offset:34816
	ds_read_b128 v[162:165], v252 offset:35840
	global_load_lds_dwordx4 v134, s[100:101]
	ds_read_b128 v[166:169], v252 offset:49152
	ds_read_b128 v[170:173], v252 offset:50176
	ds_read_b128 v[174:177], v252 offset:51200
	ds_read_b128 v[186:189], v252 offset:52224
	ds_read_b128 v[190:193], v153 offset:32768
	ds_read_b128 v[194:197], v153 offset:33792
	ds_read_b128 v[198:201], v153 offset:34816
	ds_read_b128 v[202:205], v153 offset:35840
	ds_read_b128 v[206:209], v153 offset:36864
	ds_read_b128 v[210:213], v153 offset:37888
	ds_read_b128 v[214:217], v153 offset:38912
	ds_read_b128 v[218:221], v153 offset:39936
	s_waitcnt vmcnt(8)
	s_waitcnt lgkmcnt(0)
	s_barrier
	v_mfma_f32_16x16x32_bf16 v[128:131], v[144:147], v[190:193], v[128:131]
	v_mfma_f32_16x16x32_bf16 v[128:131], v[154:157], v[194:197], v[128:131]
	v_mfma_f32_16x16x32_bf16 v[124:127], v[158:161], v[190:193], v[124:127]
	v_mfma_f32_16x16x32_bf16 v[124:127], v[162:165], v[194:197], v[124:127]
	v_mfma_f32_16x16x32_bf16 v[112:115], v[144:147], v[198:201], v[112:115]
	v_mfma_f32_16x16x32_bf16 v[112:115], v[154:157], v[202:205], v[112:115]
	v_mfma_f32_16x16x32_bf16 v[108:111], v[158:161], v[198:201], v[108:111]
	v_mfma_f32_16x16x32_bf16 v[108:111], v[162:165], v[202:205], v[108:111]
	v_mfma_f32_16x16x32_bf16 v[96:99], v[144:147], v[206:209], v[96:99]
	v_mfma_f32_16x16x32_bf16 v[96:99], v[154:157], v[210:213], v[96:99]
	v_mfma_f32_16x16x32_bf16 v[92:95], v[158:161], v[206:209], v[92:95]
	v_mfma_f32_16x16x32_bf16 v[92:95], v[162:165], v[210:213], v[92:95]
	v_mfma_f32_16x16x32_bf16 v[80:83], v[144:147], v[214:217], v[80:83]
	v_mfma_f32_16x16x32_bf16 v[80:83], v[154:157], v[218:221], v[80:83]
	v_mfma_f32_16x16x32_bf16 v[76:79], v[158:161], v[214:217], v[76:79]
	v_mfma_f32_16x16x32_bf16 v[76:79], v[162:165], v[218:221], v[76:79]
	v_mfma_f32_16x16x32_bf16 v[120:123], v[166:169], v[190:193], v[120:123]
	v_mfma_f32_16x16x32_bf16 v[120:123], v[170:173], v[194:197], v[120:123]
	v_mfma_f32_16x16x32_bf16 v[116:119], v[174:177], v[190:193], v[116:119]
	v_mfma_f32_16x16x32_bf16 v[116:119], v[186:189], v[194:197], v[116:119]
	v_mfma_f32_16x16x32_bf16 v[104:107], v[166:169], v[198:201], v[104:107]
	v_mfma_f32_16x16x32_bf16 v[104:107], v[170:173], v[202:205], v[104:107]
	v_mfma_f32_16x16x32_bf16 v[100:103], v[174:177], v[198:201], v[100:103]
	v_mfma_f32_16x16x32_bf16 v[100:103], v[186:189], v[202:205], v[100:103]
	v_mfma_f32_16x16x32_bf16 v[88:91], v[166:169], v[206:209], v[88:91]
	v_mfma_f32_16x16x32_bf16 v[88:91], v[170:173], v[210:213], v[88:91]
	v_mfma_f32_16x16x32_bf16 v[84:87], v[174:177], v[206:209], v[84:87]
	v_mfma_f32_16x16x32_bf16 v[84:87], v[186:189], v[210:213], v[84:87]
	v_mfma_f32_16x16x32_bf16 v[72:75], v[166:169], v[214:217], v[72:75]
	v_mfma_f32_16x16x32_bf16 v[72:75], v[170:173], v[218:221], v[72:75]
	v_mfma_f32_16x16x32_bf16 v[68:71], v[174:177], v[214:217], v[68:71]
	v_mfma_f32_16x16x32_bf16 v[68:71], v[186:189], v[218:221], v[68:71]
	s_barrier
	s_add_u32 s28, s28, 0x80
	s_addc_u32 s29, s29, 0
	s_add_i32 m0, s38, 0x18000
	ds_read_b128 v[190:193], v153 offset:49152
	ds_read_b128 v[194:197], v153 offset:50176
	global_load_lds_dwordx4 v136, s[28:29]
	s_add_i32 m0, s38, 0x1a000
	s_add_u32 s98, s98, 0x80
	s_addc_u32 s99, s99, 0
	ds_read_b128 v[198:201], v153 offset:51200
	global_load_lds_dwordx4 v132, s[28:29]
	s_add_i32 m0, s38, 0x1c000
	ds_read_b128 v[202:205], v153 offset:52224
	ds_read_b128 v[206:209], v153 offset:53248
	global_load_lds_dwordx4 v136, s[98:99]
	s_add_i32 m0, s38, 0x1e000
	s_add_u32 s30, s30, 0x80
	s_addc_u32 s31, s31, 0
	ds_read_b128 v[210:213], v153 offset:54272
	ds_read_b128 v[214:217], v153 offset:55296
	global_load_lds_dwordx4 v132, s[98:99]
	s_mov_b32 m0, s45
	ds_read_b128 v[218:221], v153 offset:56320
	global_load_lds_dwordx4 v138, s[30:31]
	s_mov_b32 m0, s46
	s_nop 0
	global_load_lds_dwordx4 v134, s[30:31]
	s_waitcnt vmcnt(8)
	s_waitcnt lgkmcnt(0)
	s_barrier
	v_mfma_f32_16x16x32_bf16 v[64:67], v[144:147], v[190:193], v[64:67]
	v_mfma_f32_16x16x32_bf16 v[64:67], v[154:157], v[194:197], v[64:67]
	v_mfma_f32_16x16x32_bf16 v[60:63], v[158:161], v[190:193], v[60:63]
	v_mfma_f32_16x16x32_bf16 v[60:63], v[162:165], v[194:197], v[60:63]
	v_mfma_f32_16x16x32_bf16 v[48:51], v[144:147], v[198:201], v[48:51]
	v_mfma_f32_16x16x32_bf16 v[48:51], v[154:157], v[202:205], v[48:51]
	v_mfma_f32_16x16x32_bf16 v[44:47], v[158:161], v[198:201], v[44:47]
	v_mfma_f32_16x16x32_bf16 v[44:47], v[162:165], v[202:205], v[44:47]
	v_mfma_f32_16x16x32_bf16 v[32:35], v[144:147], v[206:209], v[32:35]
	v_mfma_f32_16x16x32_bf16 v[32:35], v[154:157], v[210:213], v[32:35]
	v_mfma_f32_16x16x32_bf16 v[28:31], v[158:161], v[206:209], v[28:31]
	v_mfma_f32_16x16x32_bf16 v[28:31], v[162:165], v[210:213], v[28:31]
	v_mfma_f32_16x16x32_bf16 v[16:19], v[144:147], v[214:217], v[16:19]
	v_mfma_f32_16x16x32_bf16 v[16:19], v[154:157], v[218:221], v[16:19]
	v_mfma_f32_16x16x32_bf16 v[12:15], v[158:161], v[214:217], v[12:15]
	v_mfma_f32_16x16x32_bf16 v[12:15], v[162:165], v[218:221], v[12:15]
	v_mfma_f32_16x16x32_bf16 v[56:59], v[166:169], v[190:193], v[56:59]
	v_mfma_f32_16x16x32_bf16 v[56:59], v[170:173], v[194:197], v[56:59]
	v_mfma_f32_16x16x32_bf16 v[52:55], v[174:177], v[190:193], v[52:55]
	v_mfma_f32_16x16x32_bf16 v[52:55], v[186:189], v[194:197], v[52:55]
	v_mfma_f32_16x16x32_bf16 v[40:43], v[166:169], v[198:201], v[40:43]
	v_mfma_f32_16x16x32_bf16 v[40:43], v[170:173], v[202:205], v[40:43]
	v_mfma_f32_16x16x32_bf16 v[36:39], v[174:177], v[198:201], v[36:39]
	v_mfma_f32_16x16x32_bf16 v[36:39], v[186:189], v[202:205], v[36:39]
	v_mfma_f32_16x16x32_bf16 v[24:27], v[166:169], v[206:209], v[24:27]
	v_mfma_f32_16x16x32_bf16 v[24:27], v[170:173], v[210:213], v[24:27]
	v_mfma_f32_16x16x32_bf16 v[20:23], v[174:177], v[206:209], v[20:23]
	v_mfma_f32_16x16x32_bf16 v[20:23], v[186:189], v[210:213], v[20:23]
	v_mfma_f32_16x16x32_bf16 v[8:11], v[166:169], v[214:217], v[8:11]
	v_mfma_f32_16x16x32_bf16 v[8:11], v[170:173], v[218:221], v[8:11]
	v_mfma_f32_16x16x32_bf16 v[4:7], v[174:177], v[214:217], v[4:7]
	v_mfma_f32_16x16x32_bf16 v[4:7], v[186:189], v[218:221], v[4:7]
	s_barrier
	s_add_i32 s20, s20, 2
	s_add_u32 s10, s10, 0x100
	s_addc_u32 s11, s11, 0
	s_add_u32 s0, s0, 0x100
	s_addc_u32 s1, s1, 0
	s_cmp_gt_u32 s20, 61
	s_cbranch_scc0 .LBB0_1226
	s_and_b64 vcc, exec, s[48:49]
	s_cbranch_vccz .LBB0_1229
	s_barrier
